# P4: the two sample rows of a workgroup folded into the hand-written row pipeline (one wave per row, prefetched during the last prompt row); the LDS-barrier version is skipped
# speedup vs baseline: 1.0349x; 1.0033x over previous
; __device__ __forceinline__ float siluf_(float x) { return x * __builtin_amdgcn_rcpf(1.f + __expf(-x)); }
; __device__ __forceinline__ void mix_finalize_ssd(size_t row, bf16_t* MIX, const bf16_t* XBC, const bf16_t* PROJ, const float* d_skip, const float* ssd_norm_w, int lane, bf16_t* ssd_dst) {
;     bf16_t* mp = MIX + row * DMIX;
;     {
;         u32x4 yv[4], xv[4], zv[4]; float dsk[4];
; #pragma unroll
;         for (int k = 0; k < 4; ++k) { const int c = (k * 64 + lane) * 8;
;             yv[k] = *(const u32x4*)(mp + c); xv[k] = *(const u32x4*)(XBC + row * XBCW + c); zv[k] = *(const u32x4*)(PROJ + row * NPROJ + CZ + c);
;             dsk[k] = d_skip[c >> 6]; }
;         float s = 0.f;
; #pragma unroll
;         for (int k = 0; k < 4; ++k) { float f[8], xf[8], zf[8]; unpack8(yv[k], f); unpack8(xv[k], xf); unpack8(zv[k], zf);
; #pragma unroll
;             for (int e = 0; e < 8; ++e) { f[e] = (f[e] + dsk[k] * xf[e]) * siluf_(zf[e]); s += f[e] * f[e]; }
;             yv[k] = pack8(f); }
; __global__ void __launch_bounds__(512, 2) mk_fwd(Args args) {
;     ...
;         for (int m = bx * 8 + wave; m < MP; m += G * 8) mix_finalize_ssd((size_t)m, MIX, XBC, PROJ, d_skip, ssd_norm_w, lane, (psel == 3) ? XN + (size_t)m * DM : MIX + (size_t)m * DMIX);
.LBB0_545:
	s_cmp_lt_i32 s88, 5
	s_cselect_b64 s[4:5], -1, 0
	s_and_b64 s[0:1], s[4:5], s[0:1]
	s_andn2_b64 vcc, exec, s[0:1]
	s_cbranch_vccnz .LBB0_561
	s_mov_b64 s[8:9], s[96:97]
	s_waitcnt vmcnt(0)
	v_mov_b32_e32 v0, v212
	s_lshl_b32 s4, s2, 3
	v_readfirstlane_b32 s16, v0
	s_ashr_i32 s3, s16, 6
	s_add_i32 s10, s3, s4
	s_cmpk_gt_i32 s10, 0x1fff
	v_and_b32_e32 v54, 63, v0
	s_cbranch_scc1 .LBB0_556
	s_load_dwordx2 s[12:13], s[8:9], 0xd0
	s_load_dwordx4 s[4:7], s[8:9], 0x60
	v_lshlrev_b32_e32 v50, 4, v54
	v_lshlrev_b32_e32 v51, 5, v54
	v_lshrrev_b32_e32 v52, 3, v54
	v_lshlrev_b32_e32 v52, 2, v52
	v_mov_b32_e32 v46, 0xbfb8aa3b
	v_mov_b32_e32 v47, 1.0
	v_mov_b32_e32 v48, 0x3727c5ac
	s_waitcnt lgkmcnt(0)
	s_add_u32 s22, s6, 0x1000
	s_addc_u32 s23, s7, 0
	global_load_dwordx4 v[0:3], v51, s[6:7] offset:0
	global_load_dwordx4 v[4:7], v51, s[6:7] offset:16
	global_load_dwordx4 v[8:11], v51, s[6:7] offset:2048
	global_load_dwordx4 v[12:15], v51, s[6:7] offset:2064
	global_load_dwordx4 v[16:19], v51, s[22:23] offset:0
	global_load_dwordx4 v[20:23], v51, s[22:23] offset:16
	global_load_dwordx4 v[24:27], v51, s[22:23] offset:2048
	global_load_dwordx4 v[28:31], v51, s[22:23] offset:2064
	global_load_dword v32, v52, s[4:5] offset:0
	global_load_dword v33, v52, s[4:5] offset:32
	global_load_dword v34, v52, s[4:5] offset:64
	global_load_dword v35, v52, s[4:5] offset:96
	s_lshl_b32 s17, s10, 13
	s_add_u32 s14, s12, 0x1acd0000
	s_addc_u32 s15, s13, 0
	s_add_u32 s14, s14, s17
	s_addc_u32 s15, s15, 0
	s_mul_i32 s17, s10, 0x1800
	s_add_u32 s18, s12, 0x135d0000
	s_addc_u32 s19, s13, 0
	s_add_u32 s18, s18, s17
	s_addc_u32 s19, s19, 0
	s_mul_i32 s17, s10, 0x4a00
	s_add_u32 s20, s12, 0x9890000
	s_addc_u32 s21, s13, 0
	s_add_u32 s20, s20, s17
	s_addc_u32 s21, s21, 0
	global_load_dwordx4 v[56:59], v50, s[14:15] offset:0
	global_load_dwordx4 v[60:63], v50, s[14:15] offset:1024
	global_load_dwordx4 v[64:67], v50, s[14:15] offset:2048
	global_load_dwordx4 v[68:71], v50, s[14:15] offset:3072
	global_load_dwordx4 v[72:75], v50, s[18:19] offset:0
	global_load_dwordx4 v[76:79], v50, s[18:19] offset:1024
	global_load_dwordx4 v[80:83], v50, s[18:19] offset:2048
	global_load_dwordx4 v[84:87], v50, s[18:19] offset:3072
	global_load_dwordx4 v[88:91], v50, s[20:21] offset:0
	global_load_dwordx4 v[92:95], v50, s[20:21] offset:1024
	global_load_dwordx4 v[96:99], v50, s[20:21] offset:2048
	global_load_dwordx4 v[100:103], v50, s[20:21] offset:3072
	s_mov_b32 s26, s14
	s_mov_b32 s27, s15
	s_add_u32 s14, s14, 0x1000000
	s_addc_u32 s15, s15, 0
	s_add_u32 s18, s18, 0xc00000
	s_addc_u32 s19, s19, 0
	s_add_u32 s20, s20, 0x2500000
	s_addc_u32 s21, s21, 0
	global_load_dwordx4 v[104:107], v50, s[14:15] offset:0
	global_load_dwordx4 v[108:111], v50, s[14:15] offset:1024
	global_load_dwordx4 v[112:115], v50, s[14:15] offset:2048
	global_load_dwordx4 v[116:119], v50, s[14:15] offset:3072
	global_load_dwordx4 v[120:123], v50, s[18:19] offset:0
	global_load_dwordx4 v[124:127], v50, s[18:19] offset:1024
	global_load_dwordx4 v[128:131], v50, s[18:19] offset:2048
	global_load_dwordx4 v[132:135], v50, s[18:19] offset:3072
	global_load_dwordx4 v[136:139], v50, s[20:21] offset:0
	global_load_dwordx4 v[140:143], v50, s[20:21] offset:1024
	global_load_dwordx4 v[144:147], v50, s[20:21] offset:2048
	global_load_dwordx4 v[148:151], v50, s[20:21] offset:3072
	s_mov_b32 s12, s14
	s_mov_b32 s13, s15
	s_add_u32 s14, s14, 0x1000000
	s_addc_u32 s15, s15, 0
	s_add_u32 s18, s18, 0xc00000
	s_addc_u32 s19, s19, 0
	s_add_u32 s20, s20, 0x2500000
	s_addc_u32 s21, s21, 0
	s_waitcnt vmcnt(12)
	v_mov_b32_e32 v44, 0
	v_mov_b32_e32 v45, 0
	v_lshlrev_b32_e32 v184, 16, v56
	v_and_b32_e32 v185, 0xffff0000, v56
	v_lshlrev_b32_e32 v186, 16, v57
	v_and_b32_e32 v187, 0xffff0000, v57
	v_lshlrev_b32_e32 v188, 16, v58
	v_and_b32_e32 v189, 0xffff0000, v58
	v_lshlrev_b32_e32 v190, 16, v59
	v_and_b32_e32 v191, 0xffff0000, v59
	v_lshlrev_b32_e32 v192, 16, v72
	v_and_b32_e32 v193, 0xffff0000, v72
	v_lshlrev_b32_e32 v194, 16, v73
	v_and_b32_e32 v195, 0xffff0000, v73
	v_lshlrev_b32_e32 v196, 16, v74
	v_and_b32_e32 v197, 0xffff0000, v74
	v_lshlrev_b32_e32 v198, 16, v75
	v_and_b32_e32 v199, 0xffff0000, v75
	v_lshlrev_b32_e32 v200, 16, v88
	v_and_b32_e32 v201, 0xffff0000, v88
	v_lshlrev_b32_e32 v202, 16, v89
	v_and_b32_e32 v203, 0xffff0000, v89
	v_lshlrev_b32_e32 v204, 16, v90
	v_and_b32_e32 v205, 0xffff0000, v90
	v_lshlrev_b32_e32 v206, 16, v91
	v_and_b32_e32 v207, 0xffff0000, v91
	v_pk_fma_f32 v[184:185], v[192:193], v[32:33], v[184:185] op_sel:[0,0,0] op_sel_hi:[1,0,1]
	v_pk_fma_f32 v[186:187], v[194:195], v[32:33], v[186:187] op_sel:[0,0,0] op_sel_hi:[1,0,1]
	v_pk_fma_f32 v[188:189], v[196:197], v[32:33], v[188:189] op_sel:[0,0,0] op_sel_hi:[1,0,1]
	v_pk_fma_f32 v[190:191], v[198:199], v[32:33], v[190:191] op_sel:[0,0,0] op_sel_hi:[1,0,1]
	v_pk_mul_f32 v[36:37], v[200:201], v[46:47] op_sel:[0,0] op_sel_hi:[1,0]
	v_pk_mul_f32 v[38:39], v[202:203], v[46:47] op_sel:[0,0] op_sel_hi:[1,0]
	v_pk_mul_f32 v[40:41], v[204:205], v[46:47] op_sel:[0,0] op_sel_hi:[1,0]
	v_pk_mul_f32 v[42:43], v[206:207], v[46:47] op_sel:[0,0] op_sel_hi:[1,0]
	v_exp_f32_e32 v36, v36
	v_exp_f32_e32 v37, v37
	v_exp_f32_e32 v38, v38
	v_exp_f32_e32 v39, v39
	v_exp_f32_e32 v40, v40
	v_exp_f32_e32 v41, v41
	v_exp_f32_e32 v42, v42
	v_exp_f32_e32 v43, v43
	v_pk_add_f32 v[36:37], v[36:37], v[46:47] op_sel:[0,1] op_sel_hi:[1,1]
	v_pk_add_f32 v[38:39], v[38:39], v[46:47] op_sel:[0,1] op_sel_hi:[1,1]
	v_pk_add_f32 v[40:41], v[40:41], v[46:47] op_sel:[0,1] op_sel_hi:[1,1]
	v_pk_add_f32 v[42:43], v[42:43], v[46:47] op_sel:[0,1] op_sel_hi:[1,1]
	v_rcp_f32_e32 v36, v36
; __device__ __forceinline__ float siluf_(float x) { return x * __builtin_amdgcn_rcpf(1.f + __expf(-x)); }
; __device__ __forceinline__ void mix_finalize_ssd(size_t row, bf16_t* MIX, const bf16_t* XBC, const bf16_t* PROJ, const float* d_skip, const float* ssd_norm_w, int lane, bf16_t* ssd_dst) {
;     ...
;         for (int k = 0; k < 4; ++k) { float f[8], xf[8], zf[8]; unpack8(yv[k], f); unpack8(xv[k], xf); unpack8(zv[k], zf);
; #pragma unroll
;             for (int e = 0; e < 8; ++e) { f[e] = (f[e] + dsk[k] * xf[e]) * siluf_(zf[e]); s += f[e] * f[e]; }
;             yv[k] = pack8(f); }
	v_rcp_f32_e32 v37, v37
	v_rcp_f32_e32 v38, v38
	v_rcp_f32_e32 v39, v39
	v_rcp_f32_e32 v40, v40
	v_rcp_f32_e32 v41, v41
	v_rcp_f32_e32 v42, v42
	v_rcp_f32_e32 v43, v43
	v_pk_mul_f32 v[36:37], v[200:201], v[36:37]
	v_pk_mul_f32 v[38:39], v[202:203], v[38:39]
	v_pk_mul_f32 v[40:41], v[204:205], v[40:41]
	v_pk_mul_f32 v[42:43], v[206:207], v[42:43]
	v_pk_mul_f32 v[184:185], v[184:185], v[36:37]
	v_pk_mul_f32 v[186:187], v[186:187], v[38:39]
	v_pk_mul_f32 v[188:189], v[188:189], v[40:41]
	v_pk_mul_f32 v[190:191], v[190:191], v[42:43]
	v_pk_fma_f32 v[44:45], v[184:185], v[184:185], v[44:45]
	v_pk_fma_f32 v[44:45], v[186:187], v[186:187], v[44:45]
	v_pk_fma_f32 v[44:45], v[188:189], v[188:189], v[44:45]
	v_pk_fma_f32 v[44:45], v[190:191], v[190:191], v[44:45]
	v_cvt_pk_bf16_f32 v152, v184, v185
	v_cvt_pk_bf16_f32 v153, v186, v187
	v_cvt_pk_bf16_f32 v154, v188, v189
	v_cvt_pk_bf16_f32 v155, v190, v191
	v_lshlrev_b32_e32 v184, 16, v60
	v_and_b32_e32 v185, 0xffff0000, v60
	v_lshlrev_b32_e32 v186, 16, v61
	v_and_b32_e32 v187, 0xffff0000, v61
	v_lshlrev_b32_e32 v188, 16, v62
	v_and_b32_e32 v189, 0xffff0000, v62
	v_lshlrev_b32_e32 v190, 16, v63
	v_and_b32_e32 v191, 0xffff0000, v63
	v_lshlrev_b32_e32 v192, 16, v76
	v_and_b32_e32 v193, 0xffff0000, v76
	v_lshlrev_b32_e32 v194, 16, v77
	v_and_b32_e32 v195, 0xffff0000, v77
	v_lshlrev_b32_e32 v196, 16, v78
	v_and_b32_e32 v197, 0xffff0000, v78
	v_lshlrev_b32_e32 v198, 16, v79
	v_and_b32_e32 v199, 0xffff0000, v79
	v_lshlrev_b32_e32 v200, 16, v92
	v_and_b32_e32 v201, 0xffff0000, v92
	v_lshlrev_b32_e32 v202, 16, v93
	v_and_b32_e32 v203, 0xffff0000, v93
	v_lshlrev_b32_e32 v204, 16, v94
	v_and_b32_e32 v205, 0xffff0000, v94
	v_lshlrev_b32_e32 v206, 16, v95
	v_and_b32_e32 v207, 0xffff0000, v95
	v_pk_fma_f32 v[184:185], v[192:193], v[32:33], v[184:185] op_sel:[0,1,0] op_sel_hi:[1,1,1]
	v_pk_fma_f32 v[186:187], v[194:195], v[32:33], v[186:187] op_sel:[0,1,0] op_sel_hi:[1,1,1]
	v_pk_fma_f32 v[188:189], v[196:197], v[32:33], v[188:189] op_sel:[0,1,0] op_sel_hi:[1,1,1]
	v_pk_fma_f32 v[190:191], v[198:199], v[32:33], v[190:191] op_sel:[0,1,0] op_sel_hi:[1,1,1]
	v_pk_mul_f32 v[36:37], v[200:201], v[46:47] op_sel:[0,0] op_sel_hi:[1,0]
	v_pk_mul_f32 v[38:39], v[202:203], v[46:47] op_sel:[0,0] op_sel_hi:[1,0]
	v_pk_mul_f32 v[40:41], v[204:205], v[46:47] op_sel:[0,0] op_sel_hi:[1,0]
	v_pk_mul_f32 v[42:43], v[206:207], v[46:47] op_sel:[0,0] op_sel_hi:[1,0]
	v_exp_f32_e32 v36, v36
	v_exp_f32_e32 v37, v37
	v_exp_f32_e32 v38, v38
	v_exp_f32_e32 v39, v39
	v_exp_f32_e32 v40, v40
	v_exp_f32_e32 v41, v41
	v_exp_f32_e32 v42, v42
	v_exp_f32_e32 v43, v43
	v_pk_add_f32 v[36:37], v[36:37], v[46:47] op_sel:[0,1] op_sel_hi:[1,1]
	v_pk_add_f32 v[38:39], v[38:39], v[46:47] op_sel:[0,1] op_sel_hi:[1,1]
	v_pk_add_f32 v[40:41], v[40:41], v[46:47] op_sel:[0,1] op_sel_hi:[1,1]
	v_pk_add_f32 v[42:43], v[42:43], v[46:47] op_sel:[0,1] op_sel_hi:[1,1]
	v_rcp_f32_e32 v36, v36
	v_rcp_f32_e32 v37, v37
	v_rcp_f32_e32 v38, v38
	v_rcp_f32_e32 v39, v39
	v_rcp_f32_e32 v40, v40
	v_rcp_f32_e32 v41, v41
	v_rcp_f32_e32 v42, v42
	v_rcp_f32_e32 v43, v43
	v_pk_mul_f32 v[36:37], v[200:201], v[36:37]
	v_pk_mul_f32 v[38:39], v[202:203], v[38:39]
	v_pk_mul_f32 v[40:41], v[204:205], v[40:41]
	v_pk_mul_f32 v[42:43], v[206:207], v[42:43]
	v_pk_mul_f32 v[184:185], v[184:185], v[36:37]
	v_pk_mul_f32 v[186:187], v[186:187], v[38:39]
	v_pk_mul_f32 v[188:189], v[188:189], v[40:41]
	v_pk_mul_f32 v[190:191], v[190:191], v[42:43]
	v_pk_fma_f32 v[44:45], v[184:185], v[184:185], v[44:45]
	v_pk_fma_f32 v[44:45], v[186:187], v[186:187], v[44:45]
	v_pk_fma_f32 v[44:45], v[188:189], v[188:189], v[44:45]
	v_pk_fma_f32 v[44:45], v[190:191], v[190:191], v[44:45]
	v_cvt_pk_bf16_f32 v156, v184, v185
	v_cvt_pk_bf16_f32 v157, v186, v187
	v_cvt_pk_bf16_f32 v158, v188, v189
	v_cvt_pk_bf16_f32 v159, v190, v191
	v_lshlrev_b32_e32 v184, 16, v64
	v_and_b32_e32 v185, 0xffff0000, v64
	v_lshlrev_b32_e32 v186, 16, v65
	v_and_b32_e32 v187, 0xffff0000, v65
	v_lshlrev_b32_e32 v188, 16, v66
	v_and_b32_e32 v189, 0xffff0000, v66
	v_lshlrev_b32_e32 v190, 16, v67
	v_and_b32_e32 v191, 0xffff0000, v67
	v_lshlrev_b32_e32 v192, 16, v80
	v_and_b32_e32 v193, 0xffff0000, v80
	v_lshlrev_b32_e32 v194, 16, v81
	v_and_b32_e32 v195, 0xffff0000, v81
	v_lshlrev_b32_e32 v196, 16, v82
	v_and_b32_e32 v197, 0xffff0000, v82
	v_lshlrev_b32_e32 v198, 16, v83
	v_and_b32_e32 v199, 0xffff0000, v83
	v_lshlrev_b32_e32 v200, 16, v96
	v_and_b32_e32 v201, 0xffff0000, v96
	v_lshlrev_b32_e32 v202, 16, v97
	v_and_b32_e32 v203, 0xffff0000, v97
	v_lshlrev_b32_e32 v204, 16, v98
	v_and_b32_e32 v205, 0xffff0000, v98
	v_lshlrev_b32_e32 v206, 16, v99
	v_and_b32_e32 v207, 0xffff0000, v99
	v_pk_fma_f32 v[184:185], v[192:193], v[34:35], v[184:185] op_sel:[0,0,0] op_sel_hi:[1,0,1]
	v_pk_fma_f32 v[186:187], v[194:195], v[34:35], v[186:187] op_sel:[0,0,0] op_sel_hi:[1,0,1]
	v_pk_fma_f32 v[188:189], v[196:197], v[34:35], v[188:189] op_sel:[0,0,0] op_sel_hi:[1,0,1]
	v_pk_fma_f32 v[190:191], v[198:199], v[34:35], v[190:191] op_sel:[0,0,0] op_sel_hi:[1,0,1]
	v_pk_mul_f32 v[36:37], v[200:201], v[46:47] op_sel:[0,0] op_sel_hi:[1,0]
	v_pk_mul_f32 v[38:39], v[202:203], v[46:47] op_sel:[0,0] op_sel_hi:[1,0]
	v_pk_mul_f32 v[40:41], v[204:205], v[46:47] op_sel:[0,0] op_sel_hi:[1,0]
	v_pk_mul_f32 v[42:43], v[206:207], v[46:47] op_sel:[0,0] op_sel_hi:[1,0]
	v_exp_f32_e32 v36, v36
	v_exp_f32_e32 v37, v37
	v_exp_f32_e32 v38, v38
	v_exp_f32_e32 v39, v39
	v_exp_f32_e32 v40, v40
	v_exp_f32_e32 v41, v41
	v_exp_f32_e32 v42, v42
	v_exp_f32_e32 v43, v43
	v_pk_add_f32 v[36:37], v[36:37], v[46:47] op_sel:[0,1] op_sel_hi:[1,1]
	v_pk_add_f32 v[38:39], v[38:39], v[46:47] op_sel:[0,1] op_sel_hi:[1,1]
; __device__ __forceinline__ float siluf_(float x) { return x * __builtin_amdgcn_rcpf(1.f + __expf(-x)); }
; __device__ __forceinline__ float wave_sum(float v) {
; #pragma unroll
;     for (int o = 1; o < 64; o <<= 1) v += __shfl_xor(v, o);
;     return v;
; __device__ __forceinline__ void mix_finalize_ssd(size_t row, bf16_t* MIX, const bf16_t* XBC, const bf16_t* PROJ, const float* d_skip, const float* ssd_norm_w, int lane, bf16_t* ssd_dst) {
;     ...
;         for (int k = 0; k < 4; ++k) { float f[8], xf[8], zf[8]; unpack8(yv[k], f); unpack8(xv[k], xf); unpack8(zv[k], zf);
; #pragma unroll
;             for (int e = 0; e < 8; ++e) { f[e] = (f[e] + dsk[k] * xf[e]) * siluf_(zf[e]); s += f[e] * f[e]; }
;             yv[k] = pack8(f); }
;         const float r = rsqrtf(wave_sum(s) * (1.f / DM) + EPS);
; #pragma unroll 1
;         for (int k = 0; k < 4; ++k) { const int c = (k * 64 + lane) * 8;
;             const f32x4 w0 = *(const f32x4*)(ssd_norm_w + c), w1 = *(const f32x4*)(ssd_norm_w + c + 4);
;             const u32x4 yk = (k == 0) ? yv[0] : (k == 1) ? yv[1] : (k == 2) ? yv[2] : yv[3];
;             float f[8]; unpack8(yk, f);
;             float o[8]; o[0] = f[0] * r * w0.x; o[1] = f[1] * r * w0.y; o[2] = f[2] * r * w0.z; o[3] = f[3] * r * w0.w;
;             o[4] = f[4] * r * w1.x; o[5] = f[5] * r * w1.y; o[6] = f[6] * r * w1.z; o[7] = f[7] * r * w1.w;
;             *(u32x4*)(ssd_dst + c) = pack8(o); }
	v_pk_add_f32 v[40:41], v[40:41], v[46:47] op_sel:[0,1] op_sel_hi:[1,1]
	v_pk_add_f32 v[42:43], v[42:43], v[46:47] op_sel:[0,1] op_sel_hi:[1,1]
	v_rcp_f32_e32 v36, v36
	v_rcp_f32_e32 v37, v37
	v_rcp_f32_e32 v38, v38
	v_rcp_f32_e32 v39, v39
	v_rcp_f32_e32 v40, v40
	v_rcp_f32_e32 v41, v41
	v_rcp_f32_e32 v42, v42
	v_rcp_f32_e32 v43, v43
	v_pk_mul_f32 v[36:37], v[200:201], v[36:37]
	v_pk_mul_f32 v[38:39], v[202:203], v[38:39]
	v_pk_mul_f32 v[40:41], v[204:205], v[40:41]
	v_pk_mul_f32 v[42:43], v[206:207], v[42:43]
	v_pk_mul_f32 v[184:185], v[184:185], v[36:37]
	v_pk_mul_f32 v[186:187], v[186:187], v[38:39]
	v_pk_mul_f32 v[188:189], v[188:189], v[40:41]
	v_pk_mul_f32 v[190:191], v[190:191], v[42:43]
	v_pk_fma_f32 v[44:45], v[184:185], v[184:185], v[44:45]
	v_pk_fma_f32 v[44:45], v[186:187], v[186:187], v[44:45]
	v_pk_fma_f32 v[44:45], v[188:189], v[188:189], v[44:45]
	v_pk_fma_f32 v[44:45], v[190:191], v[190:191], v[44:45]
	v_cvt_pk_bf16_f32 v160, v184, v185
	v_cvt_pk_bf16_f32 v161, v186, v187
	v_cvt_pk_bf16_f32 v162, v188, v189
	v_cvt_pk_bf16_f32 v163, v190, v191
	v_lshlrev_b32_e32 v184, 16, v68
	v_and_b32_e32 v185, 0xffff0000, v68
	v_lshlrev_b32_e32 v186, 16, v69
	v_and_b32_e32 v187, 0xffff0000, v69
	v_lshlrev_b32_e32 v188, 16, v70
	v_and_b32_e32 v189, 0xffff0000, v70
	v_lshlrev_b32_e32 v190, 16, v71
	v_and_b32_e32 v191, 0xffff0000, v71
	v_lshlrev_b32_e32 v192, 16, v84
	v_and_b32_e32 v193, 0xffff0000, v84
	v_lshlrev_b32_e32 v194, 16, v85
	v_and_b32_e32 v195, 0xffff0000, v85
	v_lshlrev_b32_e32 v196, 16, v86
	v_and_b32_e32 v197, 0xffff0000, v86
	v_lshlrev_b32_e32 v198, 16, v87
	v_and_b32_e32 v199, 0xffff0000, v87
	v_lshlrev_b32_e32 v200, 16, v100
	v_and_b32_e32 v201, 0xffff0000, v100
	v_lshlrev_b32_e32 v202, 16, v101
	v_and_b32_e32 v203, 0xffff0000, v101
	v_lshlrev_b32_e32 v204, 16, v102
	v_and_b32_e32 v205, 0xffff0000, v102
	v_lshlrev_b32_e32 v206, 16, v103
	v_and_b32_e32 v207, 0xffff0000, v103
	v_pk_fma_f32 v[184:185], v[192:193], v[34:35], v[184:185] op_sel:[0,1,0] op_sel_hi:[1,1,1]
	v_pk_fma_f32 v[186:187], v[194:195], v[34:35], v[186:187] op_sel:[0,1,0] op_sel_hi:[1,1,1]
	v_pk_fma_f32 v[188:189], v[196:197], v[34:35], v[188:189] op_sel:[0,1,0] op_sel_hi:[1,1,1]
	v_pk_fma_f32 v[190:191], v[198:199], v[34:35], v[190:191] op_sel:[0,1,0] op_sel_hi:[1,1,1]
	v_pk_mul_f32 v[36:37], v[200:201], v[46:47] op_sel:[0,0] op_sel_hi:[1,0]
	v_pk_mul_f32 v[38:39], v[202:203], v[46:47] op_sel:[0,0] op_sel_hi:[1,0]
	v_pk_mul_f32 v[40:41], v[204:205], v[46:47] op_sel:[0,0] op_sel_hi:[1,0]
	v_pk_mul_f32 v[42:43], v[206:207], v[46:47] op_sel:[0,0] op_sel_hi:[1,0]
	v_exp_f32_e32 v36, v36
	v_exp_f32_e32 v37, v37
	v_exp_f32_e32 v38, v38
	v_exp_f32_e32 v39, v39
	v_exp_f32_e32 v40, v40
	v_exp_f32_e32 v41, v41
	v_exp_f32_e32 v42, v42
	v_exp_f32_e32 v43, v43
	v_pk_add_f32 v[36:37], v[36:37], v[46:47] op_sel:[0,1] op_sel_hi:[1,1]
	v_pk_add_f32 v[38:39], v[38:39], v[46:47] op_sel:[0,1] op_sel_hi:[1,1]
	v_pk_add_f32 v[40:41], v[40:41], v[46:47] op_sel:[0,1] op_sel_hi:[1,1]
	v_pk_add_f32 v[42:43], v[42:43], v[46:47] op_sel:[0,1] op_sel_hi:[1,1]
	v_rcp_f32_e32 v36, v36
	v_rcp_f32_e32 v37, v37
	v_rcp_f32_e32 v38, v38
	v_rcp_f32_e32 v39, v39
	v_rcp_f32_e32 v40, v40
	v_rcp_f32_e32 v41, v41
	v_rcp_f32_e32 v42, v42
	v_rcp_f32_e32 v43, v43
	v_pk_mul_f32 v[36:37], v[200:201], v[36:37]
	v_pk_mul_f32 v[38:39], v[202:203], v[38:39]
	v_pk_mul_f32 v[40:41], v[204:205], v[40:41]
	v_pk_mul_f32 v[42:43], v[206:207], v[42:43]
	v_pk_mul_f32 v[184:185], v[184:185], v[36:37]
	v_pk_mul_f32 v[186:187], v[186:187], v[38:39]
	v_pk_mul_f32 v[188:189], v[188:189], v[40:41]
	v_pk_mul_f32 v[190:191], v[190:191], v[42:43]
	v_pk_fma_f32 v[44:45], v[184:185], v[184:185], v[44:45]
	v_pk_fma_f32 v[44:45], v[186:187], v[186:187], v[44:45]
	v_pk_fma_f32 v[44:45], v[188:189], v[188:189], v[44:45]
	v_pk_fma_f32 v[44:45], v[190:191], v[190:191], v[44:45]
	v_cvt_pk_bf16_f32 v164, v184, v185
	v_cvt_pk_bf16_f32 v165, v186, v187
	v_cvt_pk_bf16_f32 v166, v188, v189
	v_cvt_pk_bf16_f32 v167, v190, v191
	v_add_f32_e32 v208, v44, v45
	s_nop 1
	v_add_f32_dpp v209, v208, v208 quad_perm:[1,0,3,2] row_mask:0xf bank_mask:0xf
	s_nop 1
	v_add_f32_dpp v208, v209, v209 quad_perm:[2,3,0,1] row_mask:0xf bank_mask:0xf
	s_nop 1
	v_add_f32_dpp v209, v208, v208 row_half_mirror row_mask:0xf bank_mask:0xf
	s_nop 1
	v_add_f32_dpp v208, v209, v209 row_mirror row_mask:0xf bank_mask:0xf
	s_nop 1
	v_readlane_b32 s10, v208, 0
	v_readlane_b32 s11, v208, 16
	v_readlane_b32 s17, v208, 32
	v_readlane_b32 s24, v208, 48
	s_nop 3
	v_mov_b32_e32 v208, s10
	v_add_f32_e32 v208, s11, v208
	v_add_f32_e32 v208, s17, v208
	v_add_f32_e32 v208, s24, v208
	v_fmamk_f32 v208, v208, 0x3a000000, v48
	v_rsq_f32_e32 v49, v208
	s_nop 0
	v_lshlrev_b32_e32 v184, 16, v152
	v_and_b32_e32 v185, 0xffff0000, v152
	v_lshlrev_b32_e32 v186, 16, v153
	v_and_b32_e32 v187, 0xffff0000, v153
	v_lshlrev_b32_e32 v188, 16, v154
	v_and_b32_e32 v189, 0xffff0000, v154
	v_lshlrev_b32_e32 v190, 16, v155
	v_and_b32_e32 v191, 0xffff0000, v155
	v_pk_mul_f32 v[184:185], v[184:185], v[48:49] op_sel:[0,1] op_sel_hi:[1,1]
	v_pk_mul_f32 v[186:187], v[186:187], v[48:49] op_sel:[0,1] op_sel_hi:[1,1]
	v_pk_mul_f32 v[188:189], v[188:189], v[48:49] op_sel:[0,1] op_sel_hi:[1,1]
	v_pk_mul_f32 v[190:191], v[190:191], v[48:49] op_sel:[0,1] op_sel_hi:[1,1]
	v_pk_mul_f32 v[184:185], v[184:185], v[0:1]
	v_pk_mul_f32 v[186:187], v[186:187], v[2:3]
	v_pk_mul_f32 v[188:189], v[188:189], v[4:5]
	v_pk_mul_f32 v[190:191], v[190:191], v[6:7]
	v_cvt_pk_bf16_f32 v168, v184, v185
	v_cvt_pk_bf16_f32 v169, v186, v187
	v_cvt_pk_bf16_f32 v170, v188, v189
	v_cvt_pk_bf16_f32 v171, v190, v191
; __device__ __forceinline__ float siluf_(float x) { return x * __builtin_amdgcn_rcpf(1.f + __expf(-x)); }
; __device__ __forceinline__ void mix_finalize_ssd(size_t row, bf16_t* MIX, const bf16_t* XBC, const bf16_t* PROJ, const float* d_skip, const float* ssd_norm_w, int lane, bf16_t* ssd_dst) {
;     ...
;         for (int k = 0; k < 4; ++k) { const int c = (k * 64 + lane) * 8;
;             yv[k] = *(const u32x4*)(mp + c); xv[k] = *(const u32x4*)(XBC + row * XBCW + c); zv[k] = *(const u32x4*)(PROJ + row * NPROJ + CZ + c);
;             dsk[k] = d_skip[c >> 6]; }
;         float s = 0.f;
; #pragma unroll
;         for (int k = 0; k < 4; ++k) { float f[8], xf[8], zf[8]; unpack8(yv[k], f); unpack8(xv[k], xf); unpack8(zv[k], zf);
; #pragma unroll
;             for (int e = 0; e < 8; ++e) { f[e] = (f[e] + dsk[k] * xf[e]) * siluf_(zf[e]); s += f[e] * f[e]; }
;             yv[k] = pack8(f); }
;     ...
;         for (int k = 0; k < 4; ++k) { const int c = (k * 64 + lane) * 8;
;             const f32x4 w0 = *(const f32x4*)(ssd_norm_w + c), w1 = *(const f32x4*)(ssd_norm_w + c + 4);
;             const u32x4 yk = (k == 0) ? yv[0] : (k == 1) ? yv[1] : (k == 2) ? yv[2] : yv[3];
;             float f[8]; unpack8(yk, f);
;             float o[8]; o[0] = f[0] * r * w0.x; o[1] = f[1] * r * w0.y; o[2] = f[2] * r * w0.z; o[3] = f[3] * r * w0.w;
;             o[4] = f[4] * r * w1.x; o[5] = f[5] * r * w1.y; o[6] = f[6] * r * w1.z; o[7] = f[7] * r * w1.w;
;             *(u32x4*)(ssd_dst + c) = pack8(o); }
	global_store_dwordx4 v50, v[168:171], s[26:27] offset:0
	v_lshlrev_b32_e32 v184, 16, v156
	v_and_b32_e32 v185, 0xffff0000, v156
	v_lshlrev_b32_e32 v186, 16, v157
	v_and_b32_e32 v187, 0xffff0000, v157
	v_lshlrev_b32_e32 v188, 16, v158
	v_and_b32_e32 v189, 0xffff0000, v158
	v_lshlrev_b32_e32 v190, 16, v159
	v_and_b32_e32 v191, 0xffff0000, v159
	v_pk_mul_f32 v[184:185], v[184:185], v[48:49] op_sel:[0,1] op_sel_hi:[1,1]
	v_pk_mul_f32 v[186:187], v[186:187], v[48:49] op_sel:[0,1] op_sel_hi:[1,1]
	v_pk_mul_f32 v[188:189], v[188:189], v[48:49] op_sel:[0,1] op_sel_hi:[1,1]
	v_pk_mul_f32 v[190:191], v[190:191], v[48:49] op_sel:[0,1] op_sel_hi:[1,1]
	v_pk_mul_f32 v[184:185], v[184:185], v[8:9]
	v_pk_mul_f32 v[186:187], v[186:187], v[10:11]
	v_pk_mul_f32 v[188:189], v[188:189], v[12:13]
	v_pk_mul_f32 v[190:191], v[190:191], v[14:15]
	v_cvt_pk_bf16_f32 v172, v184, v185
	v_cvt_pk_bf16_f32 v173, v186, v187
	v_cvt_pk_bf16_f32 v174, v188, v189
	v_cvt_pk_bf16_f32 v175, v190, v191
	global_store_dwordx4 v50, v[172:175], s[26:27] offset:1024
	v_lshlrev_b32_e32 v184, 16, v160
	v_and_b32_e32 v185, 0xffff0000, v160
	v_lshlrev_b32_e32 v186, 16, v161
	v_and_b32_e32 v187, 0xffff0000, v161
	v_lshlrev_b32_e32 v188, 16, v162
	v_and_b32_e32 v189, 0xffff0000, v162
	v_lshlrev_b32_e32 v190, 16, v163
	v_and_b32_e32 v191, 0xffff0000, v163
	v_pk_mul_f32 v[184:185], v[184:185], v[48:49] op_sel:[0,1] op_sel_hi:[1,1]
	v_pk_mul_f32 v[186:187], v[186:187], v[48:49] op_sel:[0,1] op_sel_hi:[1,1]
	v_pk_mul_f32 v[188:189], v[188:189], v[48:49] op_sel:[0,1] op_sel_hi:[1,1]
	v_pk_mul_f32 v[190:191], v[190:191], v[48:49] op_sel:[0,1] op_sel_hi:[1,1]
	v_pk_mul_f32 v[184:185], v[184:185], v[16:17]
	v_pk_mul_f32 v[186:187], v[186:187], v[18:19]
	v_pk_mul_f32 v[188:189], v[188:189], v[20:21]
	v_pk_mul_f32 v[190:191], v[190:191], v[22:23]
	v_cvt_pk_bf16_f32 v176, v184, v185
	v_cvt_pk_bf16_f32 v177, v186, v187
	v_cvt_pk_bf16_f32 v178, v188, v189
	v_cvt_pk_bf16_f32 v179, v190, v191
	global_store_dwordx4 v50, v[176:179], s[26:27] offset:2048
	v_lshlrev_b32_e32 v184, 16, v164
	v_and_b32_e32 v185, 0xffff0000, v164
	v_lshlrev_b32_e32 v186, 16, v165
	v_and_b32_e32 v187, 0xffff0000, v165
	v_lshlrev_b32_e32 v188, 16, v166
	v_and_b32_e32 v189, 0xffff0000, v166
	v_lshlrev_b32_e32 v190, 16, v167
	v_and_b32_e32 v191, 0xffff0000, v167
	v_pk_mul_f32 v[184:185], v[184:185], v[48:49] op_sel:[0,1] op_sel_hi:[1,1]
	v_pk_mul_f32 v[186:187], v[186:187], v[48:49] op_sel:[0,1] op_sel_hi:[1,1]
	v_pk_mul_f32 v[188:189], v[188:189], v[48:49] op_sel:[0,1] op_sel_hi:[1,1]
	v_pk_mul_f32 v[190:191], v[190:191], v[48:49] op_sel:[0,1] op_sel_hi:[1,1]
	v_pk_mul_f32 v[184:185], v[184:185], v[24:25]
	v_pk_mul_f32 v[186:187], v[186:187], v[26:27]
	v_pk_mul_f32 v[188:189], v[188:189], v[28:29]
	v_pk_mul_f32 v[190:191], v[190:191], v[30:31]
	v_cvt_pk_bf16_f32 v180, v184, v185
	v_cvt_pk_bf16_f32 v181, v186, v187
	v_cvt_pk_bf16_f32 v182, v188, v189
	v_cvt_pk_bf16_f32 v183, v190, v191
	global_store_dwordx4 v50, v[180:183], s[26:27] offset:3072
	global_load_dwordx4 v[56:59], v50, s[14:15] offset:0
	global_load_dwordx4 v[60:63], v50, s[14:15] offset:1024
	global_load_dwordx4 v[64:67], v50, s[14:15] offset:2048
	global_load_dwordx4 v[68:71], v50, s[14:15] offset:3072
	global_load_dwordx4 v[72:75], v50, s[18:19] offset:0
	global_load_dwordx4 v[76:79], v50, s[18:19] offset:1024
	global_load_dwordx4 v[80:83], v50, s[18:19] offset:2048
	global_load_dwordx4 v[84:87], v50, s[18:19] offset:3072
	global_load_dwordx4 v[88:91], v50, s[20:21] offset:0
	global_load_dwordx4 v[92:95], v50, s[20:21] offset:1024
	global_load_dwordx4 v[96:99], v50, s[20:21] offset:2048
	global_load_dwordx4 v[100:103], v50, s[20:21] offset:3072
	s_mov_b32 s26, s14
	s_mov_b32 s27, s15
	s_add_u32 s14, s14, 0x1000000
	s_addc_u32 s15, s15, 0
	s_add_u32 s18, s18, 0xc00000
	s_addc_u32 s19, s19, 0
	s_add_u32 s20, s20, 0x2500000
	s_addc_u32 s21, s21, 0
	s_waitcnt vmcnt(16)
	v_mov_b32_e32 v44, 0
	v_mov_b32_e32 v45, 0
	v_lshlrev_b32_e32 v184, 16, v104
	v_and_b32_e32 v185, 0xffff0000, v104
	v_lshlrev_b32_e32 v186, 16, v105
	v_and_b32_e32 v187, 0xffff0000, v105
	v_lshlrev_b32_e32 v188, 16, v106
	v_and_b32_e32 v189, 0xffff0000, v106
	v_lshlrev_b32_e32 v190, 16, v107
	v_and_b32_e32 v191, 0xffff0000, v107
	v_lshlrev_b32_e32 v192, 16, v120
	v_and_b32_e32 v193, 0xffff0000, v120
	v_lshlrev_b32_e32 v194, 16, v121
	v_and_b32_e32 v195, 0xffff0000, v121
	v_lshlrev_b32_e32 v196, 16, v122
	v_and_b32_e32 v197, 0xffff0000, v122
	v_lshlrev_b32_e32 v198, 16, v123
	v_and_b32_e32 v199, 0xffff0000, v123
	v_lshlrev_b32_e32 v200, 16, v136
	v_and_b32_e32 v201, 0xffff0000, v136
	v_lshlrev_b32_e32 v202, 16, v137
	v_and_b32_e32 v203, 0xffff0000, v137
	v_lshlrev_b32_e32 v204, 16, v138
	v_and_b32_e32 v205, 0xffff0000, v138
	v_lshlrev_b32_e32 v206, 16, v139
	v_and_b32_e32 v207, 0xffff0000, v139
	v_pk_fma_f32 v[184:185], v[192:193], v[32:33], v[184:185] op_sel:[0,0,0] op_sel_hi:[1,0,1]
	v_pk_fma_f32 v[186:187], v[194:195], v[32:33], v[186:187] op_sel:[0,0,0] op_sel_hi:[1,0,1]
	v_pk_fma_f32 v[188:189], v[196:197], v[32:33], v[188:189] op_sel:[0,0,0] op_sel_hi:[1,0,1]
	v_pk_fma_f32 v[190:191], v[198:199], v[32:33], v[190:191] op_sel:[0,0,0] op_sel_hi:[1,0,1]
	v_pk_mul_f32 v[36:37], v[200:201], v[46:47] op_sel:[0,0] op_sel_hi:[1,0]
	v_pk_mul_f32 v[38:39], v[202:203], v[46:47] op_sel:[0,0] op_sel_hi:[1,0]
	v_pk_mul_f32 v[40:41], v[204:205], v[46:47] op_sel:[0,0] op_sel_hi:[1,0]
	v_pk_mul_f32 v[42:43], v[206:207], v[46:47] op_sel:[0,0] op_sel_hi:[1,0]
	v_exp_f32_e32 v36, v36
	v_exp_f32_e32 v37, v37
	v_exp_f32_e32 v38, v38
	v_exp_f32_e32 v39, v39
	v_exp_f32_e32 v40, v40
	v_exp_f32_e32 v41, v41
	v_exp_f32_e32 v42, v42
; __device__ __forceinline__ float siluf_(float x) { return x * __builtin_amdgcn_rcpf(1.f + __expf(-x)); }
; __device__ __forceinline__ void mix_finalize_ssd(size_t row, bf16_t* MIX, const bf16_t* XBC, const bf16_t* PROJ, const float* d_skip, const float* ssd_norm_w, int lane, bf16_t* ssd_dst) {
;     ...
;         for (int k = 0; k < 4; ++k) { float f[8], xf[8], zf[8]; unpack8(yv[k], f); unpack8(xv[k], xf); unpack8(zv[k], zf);
; #pragma unroll
;             for (int e = 0; e < 8; ++e) { f[e] = (f[e] + dsk[k] * xf[e]) * siluf_(zf[e]); s += f[e] * f[e]; }
;             yv[k] = pack8(f); }
	v_exp_f32_e32 v43, v43
	v_pk_add_f32 v[36:37], v[36:37], v[46:47] op_sel:[0,1] op_sel_hi:[1,1]
	v_pk_add_f32 v[38:39], v[38:39], v[46:47] op_sel:[0,1] op_sel_hi:[1,1]
	v_pk_add_f32 v[40:41], v[40:41], v[46:47] op_sel:[0,1] op_sel_hi:[1,1]
	v_pk_add_f32 v[42:43], v[42:43], v[46:47] op_sel:[0,1] op_sel_hi:[1,1]
	v_rcp_f32_e32 v36, v36
	v_rcp_f32_e32 v37, v37
	v_rcp_f32_e32 v38, v38
	v_rcp_f32_e32 v39, v39
	v_rcp_f32_e32 v40, v40
	v_rcp_f32_e32 v41, v41
	v_rcp_f32_e32 v42, v42
	v_rcp_f32_e32 v43, v43
	v_pk_mul_f32 v[36:37], v[200:201], v[36:37]
	v_pk_mul_f32 v[38:39], v[202:203], v[38:39]
	v_pk_mul_f32 v[40:41], v[204:205], v[40:41]
	v_pk_mul_f32 v[42:43], v[206:207], v[42:43]
	v_pk_mul_f32 v[184:185], v[184:185], v[36:37]
	v_pk_mul_f32 v[186:187], v[186:187], v[38:39]
	v_pk_mul_f32 v[188:189], v[188:189], v[40:41]
	v_pk_mul_f32 v[190:191], v[190:191], v[42:43]
	v_pk_fma_f32 v[44:45], v[184:185], v[184:185], v[44:45]
	v_pk_fma_f32 v[44:45], v[186:187], v[186:187], v[44:45]
	v_pk_fma_f32 v[44:45], v[188:189], v[188:189], v[44:45]
	v_pk_fma_f32 v[44:45], v[190:191], v[190:191], v[44:45]
	v_cvt_pk_bf16_f32 v152, v184, v185
	v_cvt_pk_bf16_f32 v153, v186, v187
	v_cvt_pk_bf16_f32 v154, v188, v189
	v_cvt_pk_bf16_f32 v155, v190, v191
	v_lshlrev_b32_e32 v184, 16, v108
	v_and_b32_e32 v185, 0xffff0000, v108
	v_lshlrev_b32_e32 v186, 16, v109
	v_and_b32_e32 v187, 0xffff0000, v109
	v_lshlrev_b32_e32 v188, 16, v110
	v_and_b32_e32 v189, 0xffff0000, v110
	v_lshlrev_b32_e32 v190, 16, v111
	v_and_b32_e32 v191, 0xffff0000, v111
	v_lshlrev_b32_e32 v192, 16, v124
	v_and_b32_e32 v193, 0xffff0000, v124
	v_lshlrev_b32_e32 v194, 16, v125
	v_and_b32_e32 v195, 0xffff0000, v125
	v_lshlrev_b32_e32 v196, 16, v126
	v_and_b32_e32 v197, 0xffff0000, v126
	v_lshlrev_b32_e32 v198, 16, v127
	v_and_b32_e32 v199, 0xffff0000, v127
	v_lshlrev_b32_e32 v200, 16, v140
	v_and_b32_e32 v201, 0xffff0000, v140
	v_lshlrev_b32_e32 v202, 16, v141
	v_and_b32_e32 v203, 0xffff0000, v141
	v_lshlrev_b32_e32 v204, 16, v142
	v_and_b32_e32 v205, 0xffff0000, v142
	v_lshlrev_b32_e32 v206, 16, v143
	v_and_b32_e32 v207, 0xffff0000, v143
	v_pk_fma_f32 v[184:185], v[192:193], v[32:33], v[184:185] op_sel:[0,1,0] op_sel_hi:[1,1,1]
	v_pk_fma_f32 v[186:187], v[194:195], v[32:33], v[186:187] op_sel:[0,1,0] op_sel_hi:[1,1,1]
	v_pk_fma_f32 v[188:189], v[196:197], v[32:33], v[188:189] op_sel:[0,1,0] op_sel_hi:[1,1,1]
	v_pk_fma_f32 v[190:191], v[198:199], v[32:33], v[190:191] op_sel:[0,1,0] op_sel_hi:[1,1,1]
	v_pk_mul_f32 v[36:37], v[200:201], v[46:47] op_sel:[0,0] op_sel_hi:[1,0]
	v_pk_mul_f32 v[38:39], v[202:203], v[46:47] op_sel:[0,0] op_sel_hi:[1,0]
	v_pk_mul_f32 v[40:41], v[204:205], v[46:47] op_sel:[0,0] op_sel_hi:[1,0]
	v_pk_mul_f32 v[42:43], v[206:207], v[46:47] op_sel:[0,0] op_sel_hi:[1,0]
	v_exp_f32_e32 v36, v36
	v_exp_f32_e32 v37, v37
	v_exp_f32_e32 v38, v38
	v_exp_f32_e32 v39, v39
	v_exp_f32_e32 v40, v40
	v_exp_f32_e32 v41, v41
	v_exp_f32_e32 v42, v42
	v_exp_f32_e32 v43, v43
	v_pk_add_f32 v[36:37], v[36:37], v[46:47] op_sel:[0,1] op_sel_hi:[1,1]
	v_pk_add_f32 v[38:39], v[38:39], v[46:47] op_sel:[0,1] op_sel_hi:[1,1]
	v_pk_add_f32 v[40:41], v[40:41], v[46:47] op_sel:[0,1] op_sel_hi:[1,1]
	v_pk_add_f32 v[42:43], v[42:43], v[46:47] op_sel:[0,1] op_sel_hi:[1,1]
	v_rcp_f32_e32 v36, v36
	v_rcp_f32_e32 v37, v37
	v_rcp_f32_e32 v38, v38
	v_rcp_f32_e32 v39, v39
	v_rcp_f32_e32 v40, v40
	v_rcp_f32_e32 v41, v41
	v_rcp_f32_e32 v42, v42
	v_rcp_f32_e32 v43, v43
	v_pk_mul_f32 v[36:37], v[200:201], v[36:37]
	v_pk_mul_f32 v[38:39], v[202:203], v[38:39]
	v_pk_mul_f32 v[40:41], v[204:205], v[40:41]
	v_pk_mul_f32 v[42:43], v[206:207], v[42:43]
	v_pk_mul_f32 v[184:185], v[184:185], v[36:37]
	v_pk_mul_f32 v[186:187], v[186:187], v[38:39]
	v_pk_mul_f32 v[188:189], v[188:189], v[40:41]
	v_pk_mul_f32 v[190:191], v[190:191], v[42:43]
	v_pk_fma_f32 v[44:45], v[184:185], v[184:185], v[44:45]
	v_pk_fma_f32 v[44:45], v[186:187], v[186:187], v[44:45]
	v_pk_fma_f32 v[44:45], v[188:189], v[188:189], v[44:45]
	v_pk_fma_f32 v[44:45], v[190:191], v[190:191], v[44:45]
	v_cvt_pk_bf16_f32 v156, v184, v185
	v_cvt_pk_bf16_f32 v157, v186, v187
	v_cvt_pk_bf16_f32 v158, v188, v189
	v_cvt_pk_bf16_f32 v159, v190, v191
	v_lshlrev_b32_e32 v184, 16, v112
	v_and_b32_e32 v185, 0xffff0000, v112
	v_lshlrev_b32_e32 v186, 16, v113
	v_and_b32_e32 v187, 0xffff0000, v113
	v_lshlrev_b32_e32 v188, 16, v114
	v_and_b32_e32 v189, 0xffff0000, v114
	v_lshlrev_b32_e32 v190, 16, v115
	v_and_b32_e32 v191, 0xffff0000, v115
	v_lshlrev_b32_e32 v192, 16, v128
	v_and_b32_e32 v193, 0xffff0000, v128
	v_lshlrev_b32_e32 v194, 16, v129
	v_and_b32_e32 v195, 0xffff0000, v129
	v_lshlrev_b32_e32 v196, 16, v130
	v_and_b32_e32 v197, 0xffff0000, v130
	v_lshlrev_b32_e32 v198, 16, v131
	v_and_b32_e32 v199, 0xffff0000, v131
	v_lshlrev_b32_e32 v200, 16, v144
	v_and_b32_e32 v201, 0xffff0000, v144
	v_lshlrev_b32_e32 v202, 16, v145
	v_and_b32_e32 v203, 0xffff0000, v145
	v_lshlrev_b32_e32 v204, 16, v146
	v_and_b32_e32 v205, 0xffff0000, v146
	v_lshlrev_b32_e32 v206, 16, v147
	v_and_b32_e32 v207, 0xffff0000, v147
	v_pk_fma_f32 v[184:185], v[192:193], v[34:35], v[184:185] op_sel:[0,0,0] op_sel_hi:[1,0,1]
	v_pk_fma_f32 v[186:187], v[194:195], v[34:35], v[186:187] op_sel:[0,0,0] op_sel_hi:[1,0,1]
	v_pk_fma_f32 v[188:189], v[196:197], v[34:35], v[188:189] op_sel:[0,0,0] op_sel_hi:[1,0,1]
	v_pk_fma_f32 v[190:191], v[198:199], v[34:35], v[190:191] op_sel:[0,0,0] op_sel_hi:[1,0,1]
	v_pk_mul_f32 v[36:37], v[200:201], v[46:47] op_sel:[0,0] op_sel_hi:[1,0]
	v_pk_mul_f32 v[38:39], v[202:203], v[46:47] op_sel:[0,0] op_sel_hi:[1,0]
	v_pk_mul_f32 v[40:41], v[204:205], v[46:47] op_sel:[0,0] op_sel_hi:[1,0]
; __device__ __forceinline__ float siluf_(float x) { return x * __builtin_amdgcn_rcpf(1.f + __expf(-x)); }
; __device__ __forceinline__ float wave_sum(float v) {
; #pragma unroll
;     for (int o = 1; o < 64; o <<= 1) v += __shfl_xor(v, o);
;     return v;
; __device__ __forceinline__ void mix_finalize_ssd(size_t row, bf16_t* MIX, const bf16_t* XBC, const bf16_t* PROJ, const float* d_skip, const float* ssd_norm_w, int lane, bf16_t* ssd_dst) {
;     ...
;         for (int k = 0; k < 4; ++k) { float f[8], xf[8], zf[8]; unpack8(yv[k], f); unpack8(xv[k], xf); unpack8(zv[k], zf);
; #pragma unroll
;             for (int e = 0; e < 8; ++e) { f[e] = (f[e] + dsk[k] * xf[e]) * siluf_(zf[e]); s += f[e] * f[e]; }
;             yv[k] = pack8(f); }
;         const float r = rsqrtf(wave_sum(s) * (1.f / DM) + EPS);
; #pragma unroll 1
;         for (int k = 0; k < 4; ++k) { const int c = (k * 64 + lane) * 8;
;             const f32x4 w0 = *(const f32x4*)(ssd_norm_w + c), w1 = *(const f32x4*)(ssd_norm_w + c + 4);
;             const u32x4 yk = (k == 0) ? yv[0] : (k == 1) ? yv[1] : (k == 2) ? yv[2] : yv[3];
;             float f[8]; unpack8(yk, f);
;             float o[8]; o[0] = f[0] * r * w0.x; o[1] = f[1] * r * w0.y; o[2] = f[2] * r * w0.z; o[3] = f[3] * r * w0.w;
;             o[4] = f[4] * r * w1.x; o[5] = f[5] * r * w1.y; o[6] = f[6] * r * w1.z; o[7] = f[7] * r * w1.w;
;             *(u32x4*)(ssd_dst + c) = pack8(o); }
	v_pk_mul_f32 v[42:43], v[206:207], v[46:47] op_sel:[0,0] op_sel_hi:[1,0]
	v_exp_f32_e32 v36, v36
	v_exp_f32_e32 v37, v37
	v_exp_f32_e32 v38, v38
	v_exp_f32_e32 v39, v39
	v_exp_f32_e32 v40, v40
	v_exp_f32_e32 v41, v41
	v_exp_f32_e32 v42, v42
	v_exp_f32_e32 v43, v43
	v_pk_add_f32 v[36:37], v[36:37], v[46:47] op_sel:[0,1] op_sel_hi:[1,1]
	v_pk_add_f32 v[38:39], v[38:39], v[46:47] op_sel:[0,1] op_sel_hi:[1,1]
	v_pk_add_f32 v[40:41], v[40:41], v[46:47] op_sel:[0,1] op_sel_hi:[1,1]
	v_pk_add_f32 v[42:43], v[42:43], v[46:47] op_sel:[0,1] op_sel_hi:[1,1]
	v_rcp_f32_e32 v36, v36
	v_rcp_f32_e32 v37, v37
	v_rcp_f32_e32 v38, v38
	v_rcp_f32_e32 v39, v39
	v_rcp_f32_e32 v40, v40
	v_rcp_f32_e32 v41, v41
	v_rcp_f32_e32 v42, v42
	v_rcp_f32_e32 v43, v43
	v_pk_mul_f32 v[36:37], v[200:201], v[36:37]
	v_pk_mul_f32 v[38:39], v[202:203], v[38:39]
	v_pk_mul_f32 v[40:41], v[204:205], v[40:41]
	v_pk_mul_f32 v[42:43], v[206:207], v[42:43]
	v_pk_mul_f32 v[184:185], v[184:185], v[36:37]
	v_pk_mul_f32 v[186:187], v[186:187], v[38:39]
	v_pk_mul_f32 v[188:189], v[188:189], v[40:41]
	v_pk_mul_f32 v[190:191], v[190:191], v[42:43]
	v_pk_fma_f32 v[44:45], v[184:185], v[184:185], v[44:45]
	v_pk_fma_f32 v[44:45], v[186:187], v[186:187], v[44:45]
	v_pk_fma_f32 v[44:45], v[188:189], v[188:189], v[44:45]
	v_pk_fma_f32 v[44:45], v[190:191], v[190:191], v[44:45]
	v_cvt_pk_bf16_f32 v160, v184, v185
	v_cvt_pk_bf16_f32 v161, v186, v187
	v_cvt_pk_bf16_f32 v162, v188, v189
	v_cvt_pk_bf16_f32 v163, v190, v191
	v_lshlrev_b32_e32 v184, 16, v116
	v_and_b32_e32 v185, 0xffff0000, v116
	v_lshlrev_b32_e32 v186, 16, v117
	v_and_b32_e32 v187, 0xffff0000, v117
	v_lshlrev_b32_e32 v188, 16, v118
	v_and_b32_e32 v189, 0xffff0000, v118
	v_lshlrev_b32_e32 v190, 16, v119
	v_and_b32_e32 v191, 0xffff0000, v119
	v_lshlrev_b32_e32 v192, 16, v132
	v_and_b32_e32 v193, 0xffff0000, v132
	v_lshlrev_b32_e32 v194, 16, v133
	v_and_b32_e32 v195, 0xffff0000, v133
	v_lshlrev_b32_e32 v196, 16, v134
	v_and_b32_e32 v197, 0xffff0000, v134
	v_lshlrev_b32_e32 v198, 16, v135
	v_and_b32_e32 v199, 0xffff0000, v135
	v_lshlrev_b32_e32 v200, 16, v148
	v_and_b32_e32 v201, 0xffff0000, v148
	v_lshlrev_b32_e32 v202, 16, v149
	v_and_b32_e32 v203, 0xffff0000, v149
	v_lshlrev_b32_e32 v204, 16, v150
	v_and_b32_e32 v205, 0xffff0000, v150
	v_lshlrev_b32_e32 v206, 16, v151
	v_and_b32_e32 v207, 0xffff0000, v151
	v_pk_fma_f32 v[184:185], v[192:193], v[34:35], v[184:185] op_sel:[0,1,0] op_sel_hi:[1,1,1]
	v_pk_fma_f32 v[186:187], v[194:195], v[34:35], v[186:187] op_sel:[0,1,0] op_sel_hi:[1,1,1]
	v_pk_fma_f32 v[188:189], v[196:197], v[34:35], v[188:189] op_sel:[0,1,0] op_sel_hi:[1,1,1]
	v_pk_fma_f32 v[190:191], v[198:199], v[34:35], v[190:191] op_sel:[0,1,0] op_sel_hi:[1,1,1]
	v_pk_mul_f32 v[36:37], v[200:201], v[46:47] op_sel:[0,0] op_sel_hi:[1,0]
	v_pk_mul_f32 v[38:39], v[202:203], v[46:47] op_sel:[0,0] op_sel_hi:[1,0]
	v_pk_mul_f32 v[40:41], v[204:205], v[46:47] op_sel:[0,0] op_sel_hi:[1,0]
	v_pk_mul_f32 v[42:43], v[206:207], v[46:47] op_sel:[0,0] op_sel_hi:[1,0]
	v_exp_f32_e32 v36, v36
	v_exp_f32_e32 v37, v37
	v_exp_f32_e32 v38, v38
	v_exp_f32_e32 v39, v39
	v_exp_f32_e32 v40, v40
	v_exp_f32_e32 v41, v41
	v_exp_f32_e32 v42, v42
	v_exp_f32_e32 v43, v43
	v_pk_add_f32 v[36:37], v[36:37], v[46:47] op_sel:[0,1] op_sel_hi:[1,1]
	v_pk_add_f32 v[38:39], v[38:39], v[46:47] op_sel:[0,1] op_sel_hi:[1,1]
	v_pk_add_f32 v[40:41], v[40:41], v[46:47] op_sel:[0,1] op_sel_hi:[1,1]
	v_pk_add_f32 v[42:43], v[42:43], v[46:47] op_sel:[0,1] op_sel_hi:[1,1]
	v_rcp_f32_e32 v36, v36
	v_rcp_f32_e32 v37, v37
	v_rcp_f32_e32 v38, v38
	v_rcp_f32_e32 v39, v39
	v_rcp_f32_e32 v40, v40
	v_rcp_f32_e32 v41, v41
	v_rcp_f32_e32 v42, v42
	v_rcp_f32_e32 v43, v43
	v_pk_mul_f32 v[36:37], v[200:201], v[36:37]
	v_pk_mul_f32 v[38:39], v[202:203], v[38:39]
	v_pk_mul_f32 v[40:41], v[204:205], v[40:41]
	v_pk_mul_f32 v[42:43], v[206:207], v[42:43]
	v_pk_mul_f32 v[184:185], v[184:185], v[36:37]
	v_pk_mul_f32 v[186:187], v[186:187], v[38:39]
	v_pk_mul_f32 v[188:189], v[188:189], v[40:41]
	v_pk_mul_f32 v[190:191], v[190:191], v[42:43]
	v_pk_fma_f32 v[44:45], v[184:185], v[184:185], v[44:45]
	v_pk_fma_f32 v[44:45], v[186:187], v[186:187], v[44:45]
	v_pk_fma_f32 v[44:45], v[188:189], v[188:189], v[44:45]
	v_pk_fma_f32 v[44:45], v[190:191], v[190:191], v[44:45]
	v_cvt_pk_bf16_f32 v164, v184, v185
	v_cvt_pk_bf16_f32 v165, v186, v187
	v_cvt_pk_bf16_f32 v166, v188, v189
	v_cvt_pk_bf16_f32 v167, v190, v191
	v_add_f32_e32 v208, v44, v45
	s_nop 1
	v_add_f32_dpp v209, v208, v208 quad_perm:[1,0,3,2] row_mask:0xf bank_mask:0xf
	s_nop 1
	v_add_f32_dpp v208, v209, v209 quad_perm:[2,3,0,1] row_mask:0xf bank_mask:0xf
	s_nop 1
	v_add_f32_dpp v209, v208, v208 row_half_mirror row_mask:0xf bank_mask:0xf
	s_nop 1
	v_add_f32_dpp v208, v209, v209 row_mirror row_mask:0xf bank_mask:0xf
	s_nop 1
	v_readlane_b32 s10, v208, 0
	v_readlane_b32 s11, v208, 16
	v_readlane_b32 s17, v208, 32
	v_readlane_b32 s24, v208, 48
	s_nop 3
	v_mov_b32_e32 v208, s10
	v_add_f32_e32 v208, s11, v208
	v_add_f32_e32 v208, s17, v208
	v_add_f32_e32 v208, s24, v208
	v_fmamk_f32 v208, v208, 0x3a000000, v48
	v_rsq_f32_e32 v49, v208
	s_nop 0
	v_lshlrev_b32_e32 v184, 16, v152
	v_and_b32_e32 v185, 0xffff0000, v152
	v_lshlrev_b32_e32 v186, 16, v153
	v_and_b32_e32 v187, 0xffff0000, v153
	v_lshlrev_b32_e32 v188, 16, v154
	v_and_b32_e32 v189, 0xffff0000, v154
	v_lshlrev_b32_e32 v190, 16, v155
	v_and_b32_e32 v191, 0xffff0000, v155
	v_pk_mul_f32 v[184:185], v[184:185], v[48:49] op_sel:[0,1] op_sel_hi:[1,1]
	v_pk_mul_f32 v[186:187], v[186:187], v[48:49] op_sel:[0,1] op_sel_hi:[1,1]
	v_pk_mul_f32 v[188:189], v[188:189], v[48:49] op_sel:[0,1] op_sel_hi:[1,1]
; __device__ __forceinline__ float siluf_(float x) { return x * __builtin_amdgcn_rcpf(1.f + __expf(-x)); }
; __device__ __forceinline__ void mix_finalize_ssd(size_t row, bf16_t* MIX, const bf16_t* XBC, const bf16_t* PROJ, const float* d_skip, const float* ssd_norm_w, int lane, bf16_t* ssd_dst) {
;     ...
;         for (int k = 0; k < 4; ++k) { const int c = (k * 64 + lane) * 8;
;             yv[k] = *(const u32x4*)(mp + c); xv[k] = *(const u32x4*)(XBC + row * XBCW + c); zv[k] = *(const u32x4*)(PROJ + row * NPROJ + CZ + c);
;             dsk[k] = d_skip[c >> 6]; }
;         float s = 0.f;
; #pragma unroll
;         for (int k = 0; k < 4; ++k) { float f[8], xf[8], zf[8]; unpack8(yv[k], f); unpack8(xv[k], xf); unpack8(zv[k], zf);
; #pragma unroll
;             for (int e = 0; e < 8; ++e) { f[e] = (f[e] + dsk[k] * xf[e]) * siluf_(zf[e]); s += f[e] * f[e]; }
;             yv[k] = pack8(f); }
;     ...
;         for (int k = 0; k < 4; ++k) { const int c = (k * 64 + lane) * 8;
;             const f32x4 w0 = *(const f32x4*)(ssd_norm_w + c), w1 = *(const f32x4*)(ssd_norm_w + c + 4);
;             const u32x4 yk = (k == 0) ? yv[0] : (k == 1) ? yv[1] : (k == 2) ? yv[2] : yv[3];
;             float f[8]; unpack8(yk, f);
;             float o[8]; o[0] = f[0] * r * w0.x; o[1] = f[1] * r * w0.y; o[2] = f[2] * r * w0.z; o[3] = f[3] * r * w0.w;
;             o[4] = f[4] * r * w1.x; o[5] = f[5] * r * w1.y; o[6] = f[6] * r * w1.z; o[7] = f[7] * r * w1.w;
;             *(u32x4*)(ssd_dst + c) = pack8(o); }
	v_pk_mul_f32 v[190:191], v[190:191], v[48:49] op_sel:[0,1] op_sel_hi:[1,1]
	v_pk_mul_f32 v[184:185], v[184:185], v[0:1]
	v_pk_mul_f32 v[186:187], v[186:187], v[2:3]
	v_pk_mul_f32 v[188:189], v[188:189], v[4:5]
	v_pk_mul_f32 v[190:191], v[190:191], v[6:7]
	v_cvt_pk_bf16_f32 v168, v184, v185
	v_cvt_pk_bf16_f32 v169, v186, v187
	v_cvt_pk_bf16_f32 v170, v188, v189
	v_cvt_pk_bf16_f32 v171, v190, v191
	global_store_dwordx4 v50, v[168:171], s[12:13] offset:0
	v_lshlrev_b32_e32 v184, 16, v156
	v_and_b32_e32 v185, 0xffff0000, v156
	v_lshlrev_b32_e32 v186, 16, v157
	v_and_b32_e32 v187, 0xffff0000, v157
	v_lshlrev_b32_e32 v188, 16, v158
	v_and_b32_e32 v189, 0xffff0000, v158
	v_lshlrev_b32_e32 v190, 16, v159
	v_and_b32_e32 v191, 0xffff0000, v159
	v_pk_mul_f32 v[184:185], v[184:185], v[48:49] op_sel:[0,1] op_sel_hi:[1,1]
	v_pk_mul_f32 v[186:187], v[186:187], v[48:49] op_sel:[0,1] op_sel_hi:[1,1]
	v_pk_mul_f32 v[188:189], v[188:189], v[48:49] op_sel:[0,1] op_sel_hi:[1,1]
	v_pk_mul_f32 v[190:191], v[190:191], v[48:49] op_sel:[0,1] op_sel_hi:[1,1]
	v_pk_mul_f32 v[184:185], v[184:185], v[8:9]
	v_pk_mul_f32 v[186:187], v[186:187], v[10:11]
	v_pk_mul_f32 v[188:189], v[188:189], v[12:13]
	v_pk_mul_f32 v[190:191], v[190:191], v[14:15]
	v_cvt_pk_bf16_f32 v172, v184, v185
	v_cvt_pk_bf16_f32 v173, v186, v187
	v_cvt_pk_bf16_f32 v174, v188, v189
	v_cvt_pk_bf16_f32 v175, v190, v191
	global_store_dwordx4 v50, v[172:175], s[12:13] offset:1024
	v_lshlrev_b32_e32 v184, 16, v160
	v_and_b32_e32 v185, 0xffff0000, v160
	v_lshlrev_b32_e32 v186, 16, v161
	v_and_b32_e32 v187, 0xffff0000, v161
	v_lshlrev_b32_e32 v188, 16, v162
	v_and_b32_e32 v189, 0xffff0000, v162
	v_lshlrev_b32_e32 v190, 16, v163
	v_and_b32_e32 v191, 0xffff0000, v163
	v_pk_mul_f32 v[184:185], v[184:185], v[48:49] op_sel:[0,1] op_sel_hi:[1,1]
	v_pk_mul_f32 v[186:187], v[186:187], v[48:49] op_sel:[0,1] op_sel_hi:[1,1]
	v_pk_mul_f32 v[188:189], v[188:189], v[48:49] op_sel:[0,1] op_sel_hi:[1,1]
	v_pk_mul_f32 v[190:191], v[190:191], v[48:49] op_sel:[0,1] op_sel_hi:[1,1]
	v_pk_mul_f32 v[184:185], v[184:185], v[16:17]
	v_pk_mul_f32 v[186:187], v[186:187], v[18:19]
	v_pk_mul_f32 v[188:189], v[188:189], v[20:21]
	v_pk_mul_f32 v[190:191], v[190:191], v[22:23]
	v_cvt_pk_bf16_f32 v176, v184, v185
	v_cvt_pk_bf16_f32 v177, v186, v187
	v_cvt_pk_bf16_f32 v178, v188, v189
	v_cvt_pk_bf16_f32 v179, v190, v191
	global_store_dwordx4 v50, v[176:179], s[12:13] offset:2048
	v_lshlrev_b32_e32 v184, 16, v164
	v_and_b32_e32 v185, 0xffff0000, v164
	v_lshlrev_b32_e32 v186, 16, v165
	v_and_b32_e32 v187, 0xffff0000, v165
	v_lshlrev_b32_e32 v188, 16, v166
	v_and_b32_e32 v189, 0xffff0000, v166
	v_lshlrev_b32_e32 v190, 16, v167
	v_and_b32_e32 v191, 0xffff0000, v167
	v_pk_mul_f32 v[184:185], v[184:185], v[48:49] op_sel:[0,1] op_sel_hi:[1,1]
	v_pk_mul_f32 v[186:187], v[186:187], v[48:49] op_sel:[0,1] op_sel_hi:[1,1]
	v_pk_mul_f32 v[188:189], v[188:189], v[48:49] op_sel:[0,1] op_sel_hi:[1,1]
	v_pk_mul_f32 v[190:191], v[190:191], v[48:49] op_sel:[0,1] op_sel_hi:[1,1]
	v_pk_mul_f32 v[184:185], v[184:185], v[24:25]
	v_pk_mul_f32 v[186:187], v[186:187], v[26:27]
	v_pk_mul_f32 v[188:189], v[188:189], v[28:29]
	v_pk_mul_f32 v[190:191], v[190:191], v[30:31]
	v_cvt_pk_bf16_f32 v180, v184, v185
	v_cvt_pk_bf16_f32 v181, v186, v187
	v_cvt_pk_bf16_f32 v182, v188, v189
	v_cvt_pk_bf16_f32 v183, v190, v191
	global_store_dwordx4 v50, v[180:183], s[12:13] offset:3072
	global_load_dwordx4 v[104:107], v50, s[14:15] offset:0
	global_load_dwordx4 v[108:111], v50, s[14:15] offset:1024
	global_load_dwordx4 v[112:115], v50, s[14:15] offset:2048
	global_load_dwordx4 v[116:119], v50, s[14:15] offset:3072
	global_load_dwordx4 v[120:123], v50, s[18:19] offset:0
	global_load_dwordx4 v[124:127], v50, s[18:19] offset:1024
	global_load_dwordx4 v[128:131], v50, s[18:19] offset:2048
	global_load_dwordx4 v[132:135], v50, s[18:19] offset:3072
	global_load_dwordx4 v[136:139], v50, s[20:21] offset:0
	global_load_dwordx4 v[140:143], v50, s[20:21] offset:1024
	global_load_dwordx4 v[144:147], v50, s[20:21] offset:2048
	global_load_dwordx4 v[148:151], v50, s[20:21] offset:3072
	s_mov_b32 s12, s14
	s_mov_b32 s13, s15
	s_waitcnt vmcnt(16)
	v_mov_b32_e32 v44, 0
	v_mov_b32_e32 v45, 0
	v_lshlrev_b32_e32 v184, 16, v56
	v_and_b32_e32 v185, 0xffff0000, v56
	v_lshlrev_b32_e32 v186, 16, v57
	v_and_b32_e32 v187, 0xffff0000, v57
	v_lshlrev_b32_e32 v188, 16, v58
	v_and_b32_e32 v189, 0xffff0000, v58
	v_lshlrev_b32_e32 v190, 16, v59
	v_and_b32_e32 v191, 0xffff0000, v59
	v_lshlrev_b32_e32 v192, 16, v72
	v_and_b32_e32 v193, 0xffff0000, v72
	v_lshlrev_b32_e32 v194, 16, v73
	v_and_b32_e32 v195, 0xffff0000, v73
	v_lshlrev_b32_e32 v196, 16, v74
	v_and_b32_e32 v197, 0xffff0000, v74
	v_lshlrev_b32_e32 v198, 16, v75
	v_and_b32_e32 v199, 0xffff0000, v75
	v_lshlrev_b32_e32 v200, 16, v88
	v_and_b32_e32 v201, 0xffff0000, v88
	v_lshlrev_b32_e32 v202, 16, v89
	v_and_b32_e32 v203, 0xffff0000, v89
	v_lshlrev_b32_e32 v204, 16, v90
	v_and_b32_e32 v205, 0xffff0000, v90
	v_lshlrev_b32_e32 v206, 16, v91
	v_and_b32_e32 v207, 0xffff0000, v91
	v_pk_fma_f32 v[184:185], v[192:193], v[32:33], v[184:185] op_sel:[0,0,0] op_sel_hi:[1,0,1]
	v_pk_fma_f32 v[186:187], v[194:195], v[32:33], v[186:187] op_sel:[0,0,0] op_sel_hi:[1,0,1]
	v_pk_fma_f32 v[188:189], v[196:197], v[32:33], v[188:189] op_sel:[0,0,0] op_sel_hi:[1,0,1]
	v_pk_fma_f32 v[190:191], v[198:199], v[32:33], v[190:191] op_sel:[0,0,0] op_sel_hi:[1,0,1]
	v_pk_mul_f32 v[36:37], v[200:201], v[46:47] op_sel:[0,0] op_sel_hi:[1,0]
	v_pk_mul_f32 v[38:39], v[202:203], v[46:47] op_sel:[0,0] op_sel_hi:[1,0]
	v_pk_mul_f32 v[40:41], v[204:205], v[46:47] op_sel:[0,0] op_sel_hi:[1,0]
; __device__ __forceinline__ float siluf_(float x) { return x * __builtin_amdgcn_rcpf(1.f + __expf(-x)); }
; __device__ __forceinline__ void mix_finalize_ssd(size_t row, bf16_t* MIX, const bf16_t* XBC, const bf16_t* PROJ, const float* d_skip, const float* ssd_norm_w, int lane, bf16_t* ssd_dst) {
;     ...
;         for (int k = 0; k < 4; ++k) { float f[8], xf[8], zf[8]; unpack8(yv[k], f); unpack8(xv[k], xf); unpack8(zv[k], zf);
; #pragma unroll
;             for (int e = 0; e < 8; ++e) { f[e] = (f[e] + dsk[k] * xf[e]) * siluf_(zf[e]); s += f[e] * f[e]; }
;             yv[k] = pack8(f); }
	v_pk_mul_f32 v[42:43], v[206:207], v[46:47] op_sel:[0,0] op_sel_hi:[1,0]
	v_exp_f32_e32 v36, v36
	v_exp_f32_e32 v37, v37
	v_exp_f32_e32 v38, v38
	v_exp_f32_e32 v39, v39
	v_exp_f32_e32 v40, v40
	v_exp_f32_e32 v41, v41
	v_exp_f32_e32 v42, v42
	v_exp_f32_e32 v43, v43
	v_pk_add_f32 v[36:37], v[36:37], v[46:47] op_sel:[0,1] op_sel_hi:[1,1]
	v_pk_add_f32 v[38:39], v[38:39], v[46:47] op_sel:[0,1] op_sel_hi:[1,1]
	v_pk_add_f32 v[40:41], v[40:41], v[46:47] op_sel:[0,1] op_sel_hi:[1,1]
	v_pk_add_f32 v[42:43], v[42:43], v[46:47] op_sel:[0,1] op_sel_hi:[1,1]
	v_rcp_f32_e32 v36, v36
	v_rcp_f32_e32 v37, v37
	v_rcp_f32_e32 v38, v38
	v_rcp_f32_e32 v39, v39
	v_rcp_f32_e32 v40, v40
	v_rcp_f32_e32 v41, v41
	v_rcp_f32_e32 v42, v42
	v_rcp_f32_e32 v43, v43
	v_pk_mul_f32 v[36:37], v[200:201], v[36:37]
	v_pk_mul_f32 v[38:39], v[202:203], v[38:39]
	v_pk_mul_f32 v[40:41], v[204:205], v[40:41]
	v_pk_mul_f32 v[42:43], v[206:207], v[42:43]
	v_pk_mul_f32 v[184:185], v[184:185], v[36:37]
	v_pk_mul_f32 v[186:187], v[186:187], v[38:39]
	v_pk_mul_f32 v[188:189], v[188:189], v[40:41]
	v_pk_mul_f32 v[190:191], v[190:191], v[42:43]
	v_pk_fma_f32 v[44:45], v[184:185], v[184:185], v[44:45]
	v_pk_fma_f32 v[44:45], v[186:187], v[186:187], v[44:45]
	v_pk_fma_f32 v[44:45], v[188:189], v[188:189], v[44:45]
	v_pk_fma_f32 v[44:45], v[190:191], v[190:191], v[44:45]
	v_cvt_pk_bf16_f32 v152, v184, v185
	v_cvt_pk_bf16_f32 v153, v186, v187
	v_cvt_pk_bf16_f32 v154, v188, v189
	v_cvt_pk_bf16_f32 v155, v190, v191
	v_lshlrev_b32_e32 v184, 16, v60
	v_and_b32_e32 v185, 0xffff0000, v60
	v_lshlrev_b32_e32 v186, 16, v61
	v_and_b32_e32 v187, 0xffff0000, v61
	v_lshlrev_b32_e32 v188, 16, v62
	v_and_b32_e32 v189, 0xffff0000, v62
	v_lshlrev_b32_e32 v190, 16, v63
	v_and_b32_e32 v191, 0xffff0000, v63
	v_lshlrev_b32_e32 v192, 16, v76
	v_and_b32_e32 v193, 0xffff0000, v76
	v_lshlrev_b32_e32 v194, 16, v77
	v_and_b32_e32 v195, 0xffff0000, v77
	v_lshlrev_b32_e32 v196, 16, v78
	v_and_b32_e32 v197, 0xffff0000, v78
	v_lshlrev_b32_e32 v198, 16, v79
	v_and_b32_e32 v199, 0xffff0000, v79
	v_lshlrev_b32_e32 v200, 16, v92
	v_and_b32_e32 v201, 0xffff0000, v92
	v_lshlrev_b32_e32 v202, 16, v93
	v_and_b32_e32 v203, 0xffff0000, v93
	v_lshlrev_b32_e32 v204, 16, v94
	v_and_b32_e32 v205, 0xffff0000, v94
	v_lshlrev_b32_e32 v206, 16, v95
	v_and_b32_e32 v207, 0xffff0000, v95
	v_pk_fma_f32 v[184:185], v[192:193], v[32:33], v[184:185] op_sel:[0,1,0] op_sel_hi:[1,1,1]
	v_pk_fma_f32 v[186:187], v[194:195], v[32:33], v[186:187] op_sel:[0,1,0] op_sel_hi:[1,1,1]
	v_pk_fma_f32 v[188:189], v[196:197], v[32:33], v[188:189] op_sel:[0,1,0] op_sel_hi:[1,1,1]
	v_pk_fma_f32 v[190:191], v[198:199], v[32:33], v[190:191] op_sel:[0,1,0] op_sel_hi:[1,1,1]
	v_pk_mul_f32 v[36:37], v[200:201], v[46:47] op_sel:[0,0] op_sel_hi:[1,0]
	v_pk_mul_f32 v[38:39], v[202:203], v[46:47] op_sel:[0,0] op_sel_hi:[1,0]
	v_pk_mul_f32 v[40:41], v[204:205], v[46:47] op_sel:[0,0] op_sel_hi:[1,0]
	v_pk_mul_f32 v[42:43], v[206:207], v[46:47] op_sel:[0,0] op_sel_hi:[1,0]
	v_exp_f32_e32 v36, v36
	v_exp_f32_e32 v37, v37
	v_exp_f32_e32 v38, v38
	v_exp_f32_e32 v39, v39
	v_exp_f32_e32 v40, v40
	v_exp_f32_e32 v41, v41
	v_exp_f32_e32 v42, v42
	v_exp_f32_e32 v43, v43
	v_pk_add_f32 v[36:37], v[36:37], v[46:47] op_sel:[0,1] op_sel_hi:[1,1]
	v_pk_add_f32 v[38:39], v[38:39], v[46:47] op_sel:[0,1] op_sel_hi:[1,1]
	v_pk_add_f32 v[40:41], v[40:41], v[46:47] op_sel:[0,1] op_sel_hi:[1,1]
	v_pk_add_f32 v[42:43], v[42:43], v[46:47] op_sel:[0,1] op_sel_hi:[1,1]
	v_rcp_f32_e32 v36, v36
	v_rcp_f32_e32 v37, v37
	v_rcp_f32_e32 v38, v38
	v_rcp_f32_e32 v39, v39
	v_rcp_f32_e32 v40, v40
	v_rcp_f32_e32 v41, v41
	v_rcp_f32_e32 v42, v42
	v_rcp_f32_e32 v43, v43
	v_pk_mul_f32 v[36:37], v[200:201], v[36:37]
	v_pk_mul_f32 v[38:39], v[202:203], v[38:39]
	v_pk_mul_f32 v[40:41], v[204:205], v[40:41]
	v_pk_mul_f32 v[42:43], v[206:207], v[42:43]
	v_pk_mul_f32 v[184:185], v[184:185], v[36:37]
	v_pk_mul_f32 v[186:187], v[186:187], v[38:39]
	v_pk_mul_f32 v[188:189], v[188:189], v[40:41]
	v_pk_mul_f32 v[190:191], v[190:191], v[42:43]
	v_pk_fma_f32 v[44:45], v[184:185], v[184:185], v[44:45]
	v_pk_fma_f32 v[44:45], v[186:187], v[186:187], v[44:45]
	v_pk_fma_f32 v[44:45], v[188:189], v[188:189], v[44:45]
	v_pk_fma_f32 v[44:45], v[190:191], v[190:191], v[44:45]
	v_cvt_pk_bf16_f32 v156, v184, v185
	v_cvt_pk_bf16_f32 v157, v186, v187
	v_cvt_pk_bf16_f32 v158, v188, v189
	v_cvt_pk_bf16_f32 v159, v190, v191
	v_lshlrev_b32_e32 v184, 16, v64
	v_and_b32_e32 v185, 0xffff0000, v64
	v_lshlrev_b32_e32 v186, 16, v65
	v_and_b32_e32 v187, 0xffff0000, v65
	v_lshlrev_b32_e32 v188, 16, v66
	v_and_b32_e32 v189, 0xffff0000, v66
	v_lshlrev_b32_e32 v190, 16, v67
	v_and_b32_e32 v191, 0xffff0000, v67
	v_lshlrev_b32_e32 v192, 16, v80
	v_and_b32_e32 v193, 0xffff0000, v80
	v_lshlrev_b32_e32 v194, 16, v81
	v_and_b32_e32 v195, 0xffff0000, v81
	v_lshlrev_b32_e32 v196, 16, v82
	v_and_b32_e32 v197, 0xffff0000, v82
	v_lshlrev_b32_e32 v198, 16, v83
	v_and_b32_e32 v199, 0xffff0000, v83
	v_lshlrev_b32_e32 v200, 16, v96
	v_and_b32_e32 v201, 0xffff0000, v96
	v_lshlrev_b32_e32 v202, 16, v97
	v_and_b32_e32 v203, 0xffff0000, v97
	v_lshlrev_b32_e32 v204, 16, v98
	v_and_b32_e32 v205, 0xffff0000, v98
	v_lshlrev_b32_e32 v206, 16, v99
	v_and_b32_e32 v207, 0xffff0000, v99
	v_pk_fma_f32 v[184:185], v[192:193], v[34:35], v[184:185] op_sel:[0,0,0] op_sel_hi:[1,0,1]
	v_pk_fma_f32 v[186:187], v[194:195], v[34:35], v[186:187] op_sel:[0,0,0] op_sel_hi:[1,0,1]
	v_pk_fma_f32 v[188:189], v[196:197], v[34:35], v[188:189] op_sel:[0,0,0] op_sel_hi:[1,0,1]
	v_pk_fma_f32 v[190:191], v[198:199], v[34:35], v[190:191] op_sel:[0,0,0] op_sel_hi:[1,0,1]
; __device__ __forceinline__ float siluf_(float x) { return x * __builtin_amdgcn_rcpf(1.f + __expf(-x)); }
; __device__ __forceinline__ float wave_sum(float v) {
; #pragma unroll
;     for (int o = 1; o < 64; o <<= 1) v += __shfl_xor(v, o);
;     return v;
; __device__ __forceinline__ void mix_finalize_ssd(size_t row, bf16_t* MIX, const bf16_t* XBC, const bf16_t* PROJ, const float* d_skip, const float* ssd_norm_w, int lane, bf16_t* ssd_dst) {
;     ...
;         for (int k = 0; k < 4; ++k) { float f[8], xf[8], zf[8]; unpack8(yv[k], f); unpack8(xv[k], xf); unpack8(zv[k], zf);
; #pragma unroll
;             for (int e = 0; e < 8; ++e) { f[e] = (f[e] + dsk[k] * xf[e]) * siluf_(zf[e]); s += f[e] * f[e]; }
;             yv[k] = pack8(f); }
;         const float r = rsqrtf(wave_sum(s) * (1.f / DM) + EPS);
; #pragma unroll 1
;         for (int k = 0; k < 4; ++k) { const int c = (k * 64 + lane) * 8;
;             const f32x4 w0 = *(const f32x4*)(ssd_norm_w + c), w1 = *(const f32x4*)(ssd_norm_w + c + 4);
;             const u32x4 yk = (k == 0) ? yv[0] : (k == 1) ? yv[1] : (k == 2) ? yv[2] : yv[3];
;             float f[8]; unpack8(yk, f);
;             float o[8]; o[0] = f[0] * r * w0.x; o[1] = f[1] * r * w0.y; o[2] = f[2] * r * w0.z; o[3] = f[3] * r * w0.w;
;             o[4] = f[4] * r * w1.x; o[5] = f[5] * r * w1.y; o[6] = f[6] * r * w1.z; o[7] = f[7] * r * w1.w;
	v_pk_mul_f32 v[36:37], v[200:201], v[46:47] op_sel:[0,0] op_sel_hi:[1,0]
	v_pk_mul_f32 v[38:39], v[202:203], v[46:47] op_sel:[0,0] op_sel_hi:[1,0]
	v_pk_mul_f32 v[40:41], v[204:205], v[46:47] op_sel:[0,0] op_sel_hi:[1,0]
	v_pk_mul_f32 v[42:43], v[206:207], v[46:47] op_sel:[0,0] op_sel_hi:[1,0]
	v_exp_f32_e32 v36, v36
	v_exp_f32_e32 v37, v37
	v_exp_f32_e32 v38, v38
	v_exp_f32_e32 v39, v39
	v_exp_f32_e32 v40, v40
	v_exp_f32_e32 v41, v41
	v_exp_f32_e32 v42, v42
	v_exp_f32_e32 v43, v43
	v_pk_add_f32 v[36:37], v[36:37], v[46:47] op_sel:[0,1] op_sel_hi:[1,1]
	v_pk_add_f32 v[38:39], v[38:39], v[46:47] op_sel:[0,1] op_sel_hi:[1,1]
	v_pk_add_f32 v[40:41], v[40:41], v[46:47] op_sel:[0,1] op_sel_hi:[1,1]
	v_pk_add_f32 v[42:43], v[42:43], v[46:47] op_sel:[0,1] op_sel_hi:[1,1]
	v_rcp_f32_e32 v36, v36
	v_rcp_f32_e32 v37, v37
	v_rcp_f32_e32 v38, v38
	v_rcp_f32_e32 v39, v39
	v_rcp_f32_e32 v40, v40
	v_rcp_f32_e32 v41, v41
	v_rcp_f32_e32 v42, v42
	v_rcp_f32_e32 v43, v43
	v_pk_mul_f32 v[36:37], v[200:201], v[36:37]
	v_pk_mul_f32 v[38:39], v[202:203], v[38:39]
	v_pk_mul_f32 v[40:41], v[204:205], v[40:41]
	v_pk_mul_f32 v[42:43], v[206:207], v[42:43]
	v_pk_mul_f32 v[184:185], v[184:185], v[36:37]
	v_pk_mul_f32 v[186:187], v[186:187], v[38:39]
	v_pk_mul_f32 v[188:189], v[188:189], v[40:41]
	v_pk_mul_f32 v[190:191], v[190:191], v[42:43]
	v_pk_fma_f32 v[44:45], v[184:185], v[184:185], v[44:45]
	v_pk_fma_f32 v[44:45], v[186:187], v[186:187], v[44:45]
	v_pk_fma_f32 v[44:45], v[188:189], v[188:189], v[44:45]
	v_pk_fma_f32 v[44:45], v[190:191], v[190:191], v[44:45]
	v_cvt_pk_bf16_f32 v160, v184, v185
	v_cvt_pk_bf16_f32 v161, v186, v187
	v_cvt_pk_bf16_f32 v162, v188, v189
	v_cvt_pk_bf16_f32 v163, v190, v191
	v_lshlrev_b32_e32 v184, 16, v68
	v_and_b32_e32 v185, 0xffff0000, v68
	v_lshlrev_b32_e32 v186, 16, v69
	v_and_b32_e32 v187, 0xffff0000, v69
	v_lshlrev_b32_e32 v188, 16, v70
	v_and_b32_e32 v189, 0xffff0000, v70
	v_lshlrev_b32_e32 v190, 16, v71
	v_and_b32_e32 v191, 0xffff0000, v71
	v_lshlrev_b32_e32 v192, 16, v84
	v_and_b32_e32 v193, 0xffff0000, v84
	v_lshlrev_b32_e32 v194, 16, v85
	v_and_b32_e32 v195, 0xffff0000, v85
	v_lshlrev_b32_e32 v196, 16, v86
	v_and_b32_e32 v197, 0xffff0000, v86
	v_lshlrev_b32_e32 v198, 16, v87
	v_and_b32_e32 v199, 0xffff0000, v87
	v_lshlrev_b32_e32 v200, 16, v100
	v_and_b32_e32 v201, 0xffff0000, v100
	v_lshlrev_b32_e32 v202, 16, v101
	v_and_b32_e32 v203, 0xffff0000, v101
	v_lshlrev_b32_e32 v204, 16, v102
	v_and_b32_e32 v205, 0xffff0000, v102
	v_lshlrev_b32_e32 v206, 16, v103
	v_and_b32_e32 v207, 0xffff0000, v103
	v_pk_fma_f32 v[184:185], v[192:193], v[34:35], v[184:185] op_sel:[0,1,0] op_sel_hi:[1,1,1]
	v_pk_fma_f32 v[186:187], v[194:195], v[34:35], v[186:187] op_sel:[0,1,0] op_sel_hi:[1,1,1]
	v_pk_fma_f32 v[188:189], v[196:197], v[34:35], v[188:189] op_sel:[0,1,0] op_sel_hi:[1,1,1]
	v_pk_fma_f32 v[190:191], v[198:199], v[34:35], v[190:191] op_sel:[0,1,0] op_sel_hi:[1,1,1]
	v_pk_mul_f32 v[36:37], v[200:201], v[46:47] op_sel:[0,0] op_sel_hi:[1,0]
	v_pk_mul_f32 v[38:39], v[202:203], v[46:47] op_sel:[0,0] op_sel_hi:[1,0]
	v_pk_mul_f32 v[40:41], v[204:205], v[46:47] op_sel:[0,0] op_sel_hi:[1,0]
	v_pk_mul_f32 v[42:43], v[206:207], v[46:47] op_sel:[0,0] op_sel_hi:[1,0]
	v_exp_f32_e32 v36, v36
	v_exp_f32_e32 v37, v37
	v_exp_f32_e32 v38, v38
	v_exp_f32_e32 v39, v39
	v_exp_f32_e32 v40, v40
	v_exp_f32_e32 v41, v41
	v_exp_f32_e32 v42, v42
	v_exp_f32_e32 v43, v43
	v_pk_add_f32 v[36:37], v[36:37], v[46:47] op_sel:[0,1] op_sel_hi:[1,1]
	v_pk_add_f32 v[38:39], v[38:39], v[46:47] op_sel:[0,1] op_sel_hi:[1,1]
	v_pk_add_f32 v[40:41], v[40:41], v[46:47] op_sel:[0,1] op_sel_hi:[1,1]
	v_pk_add_f32 v[42:43], v[42:43], v[46:47] op_sel:[0,1] op_sel_hi:[1,1]
	v_rcp_f32_e32 v36, v36
	v_rcp_f32_e32 v37, v37
	v_rcp_f32_e32 v38, v38
	v_rcp_f32_e32 v39, v39
	v_rcp_f32_e32 v40, v40
	v_rcp_f32_e32 v41, v41
	v_rcp_f32_e32 v42, v42
	v_rcp_f32_e32 v43, v43
	v_pk_mul_f32 v[36:37], v[200:201], v[36:37]
	v_pk_mul_f32 v[38:39], v[202:203], v[38:39]
	v_pk_mul_f32 v[40:41], v[204:205], v[40:41]
	v_pk_mul_f32 v[42:43], v[206:207], v[42:43]
	v_pk_mul_f32 v[184:185], v[184:185], v[36:37]
	v_pk_mul_f32 v[186:187], v[186:187], v[38:39]
	v_pk_mul_f32 v[188:189], v[188:189], v[40:41]
	v_pk_mul_f32 v[190:191], v[190:191], v[42:43]
	v_pk_fma_f32 v[44:45], v[184:185], v[184:185], v[44:45]
	v_pk_fma_f32 v[44:45], v[186:187], v[186:187], v[44:45]
	v_pk_fma_f32 v[44:45], v[188:189], v[188:189], v[44:45]
	v_pk_fma_f32 v[44:45], v[190:191], v[190:191], v[44:45]
	v_cvt_pk_bf16_f32 v164, v184, v185
	v_cvt_pk_bf16_f32 v165, v186, v187
	v_cvt_pk_bf16_f32 v166, v188, v189
	v_cvt_pk_bf16_f32 v167, v190, v191
	v_add_f32_e32 v208, v44, v45
	s_nop 1
	v_add_f32_dpp v209, v208, v208 quad_perm:[1,0,3,2] row_mask:0xf bank_mask:0xf
	s_nop 1
	v_add_f32_dpp v208, v209, v209 quad_perm:[2,3,0,1] row_mask:0xf bank_mask:0xf
	s_nop 1
	v_add_f32_dpp v209, v208, v208 row_half_mirror row_mask:0xf bank_mask:0xf
	s_nop 1
	v_add_f32_dpp v208, v209, v209 row_mirror row_mask:0xf bank_mask:0xf
	s_nop 1
	v_readlane_b32 s10, v208, 0
	v_readlane_b32 s11, v208, 16
	v_readlane_b32 s17, v208, 32
	v_readlane_b32 s24, v208, 48
	s_nop 3
	v_mov_b32_e32 v208, s10
	v_add_f32_e32 v208, s11, v208
	v_add_f32_e32 v208, s17, v208
	v_add_f32_e32 v208, s24, v208
	v_fmamk_f32 v208, v208, 0x3a000000, v48
	v_rsq_f32_e32 v49, v208
	s_nop 0
	v_lshlrev_b32_e32 v184, 16, v152
	v_and_b32_e32 v185, 0xffff0000, v152
	v_lshlrev_b32_e32 v186, 16, v153
	v_and_b32_e32 v187, 0xffff0000, v153
	v_lshlrev_b32_e32 v188, 16, v154
	v_and_b32_e32 v189, 0xffff0000, v154
	v_lshlrev_b32_e32 v190, 16, v155
	v_and_b32_e32 v191, 0xffff0000, v155
; __device__ __forceinline__ void mix_finalize_ssd(size_t row, bf16_t* MIX, const bf16_t* XBC, const bf16_t* PROJ, const float* d_skip, const float* ssd_norm_w, int lane, bf16_t* ssd_dst) {
;     ...
;         for (int k = 0; k < 4; ++k) { const int c = (k * 64 + lane) * 8;
;             const f32x4 w0 = *(const f32x4*)(ssd_norm_w + c), w1 = *(const f32x4*)(ssd_norm_w + c + 4);
;             const u32x4 yk = (k == 0) ? yv[0] : (k == 1) ? yv[1] : (k == 2) ? yv[2] : yv[3];
;             float f[8]; unpack8(yk, f);
;             float o[8]; o[0] = f[0] * r * w0.x; o[1] = f[1] * r * w0.y; o[2] = f[2] * r * w0.z; o[3] = f[3] * r * w0.w;
;             o[4] = f[4] * r * w1.x; o[5] = f[5] * r * w1.y; o[6] = f[6] * r * w1.z; o[7] = f[7] * r * w1.w;
;             *(u32x4*)(ssd_dst + c) = pack8(o); }
; __global__ void __launch_bounds__(512, 2) mk_fwd(Args args) {
;     ...
;         for (int m0 = MP + 2 * bx; m0 < MT; m0 += 2 * G) {
;             const size_t m = (size_t)(m0 + (wave >> 2)); const int q = wave & 3, c = q * 512 + lane * 8;
;             bf16_t* mp = MIX + m * DMIX;
;             const u32x4 yv = *(const u32x4*)(mp + c), xv = *(const u32x4*)(XBC + m * XBCW + c), zv = *(const u32x4*)(PROJ + m * NPROJ + CZ + c);
;             const float dsk = d_skip[c >> 6]; const f32x4 w0 = *(const f32x4*)(ssd_norm_w + c), w1 = *(const f32x4*)(ssd_norm_w + c + 4);
	v_pk_mul_f32 v[184:185], v[184:185], v[48:49] op_sel:[0,1] op_sel_hi:[1,1]
	v_pk_mul_f32 v[186:187], v[186:187], v[48:49] op_sel:[0,1] op_sel_hi:[1,1]
	v_pk_mul_f32 v[188:189], v[188:189], v[48:49] op_sel:[0,1] op_sel_hi:[1,1]
	v_pk_mul_f32 v[190:191], v[190:191], v[48:49] op_sel:[0,1] op_sel_hi:[1,1]
	v_pk_mul_f32 v[184:185], v[184:185], v[0:1]
	v_pk_mul_f32 v[186:187], v[186:187], v[2:3]
	v_pk_mul_f32 v[188:189], v[188:189], v[4:5]
	v_pk_mul_f32 v[190:191], v[190:191], v[6:7]
	v_cvt_pk_bf16_f32 v168, v184, v185
	v_cvt_pk_bf16_f32 v169, v186, v187
	v_cvt_pk_bf16_f32 v170, v188, v189
	v_cvt_pk_bf16_f32 v171, v190, v191
	global_store_dwordx4 v50, v[168:171], s[26:27] offset:0
	v_lshlrev_b32_e32 v184, 16, v156
	v_and_b32_e32 v185, 0xffff0000, v156
	v_lshlrev_b32_e32 v186, 16, v157
	v_and_b32_e32 v187, 0xffff0000, v157
	v_lshlrev_b32_e32 v188, 16, v158
	v_and_b32_e32 v189, 0xffff0000, v158
	v_lshlrev_b32_e32 v190, 16, v159
	v_and_b32_e32 v191, 0xffff0000, v159
	v_pk_mul_f32 v[184:185], v[184:185], v[48:49] op_sel:[0,1] op_sel_hi:[1,1]
	v_pk_mul_f32 v[186:187], v[186:187], v[48:49] op_sel:[0,1] op_sel_hi:[1,1]
	v_pk_mul_f32 v[188:189], v[188:189], v[48:49] op_sel:[0,1] op_sel_hi:[1,1]
	v_pk_mul_f32 v[190:191], v[190:191], v[48:49] op_sel:[0,1] op_sel_hi:[1,1]
	v_pk_mul_f32 v[184:185], v[184:185], v[8:9]
	v_pk_mul_f32 v[186:187], v[186:187], v[10:11]
	v_pk_mul_f32 v[188:189], v[188:189], v[12:13]
	v_pk_mul_f32 v[190:191], v[190:191], v[14:15]
	v_cvt_pk_bf16_f32 v172, v184, v185
	v_cvt_pk_bf16_f32 v173, v186, v187
	v_cvt_pk_bf16_f32 v174, v188, v189
	v_cvt_pk_bf16_f32 v175, v190, v191
	global_store_dwordx4 v50, v[172:175], s[26:27] offset:1024
	v_lshlrev_b32_e32 v184, 16, v160
	v_and_b32_e32 v185, 0xffff0000, v160
	v_lshlrev_b32_e32 v186, 16, v161
	v_and_b32_e32 v187, 0xffff0000, v161
	v_lshlrev_b32_e32 v188, 16, v162
	v_and_b32_e32 v189, 0xffff0000, v162
	v_lshlrev_b32_e32 v190, 16, v163
	v_and_b32_e32 v191, 0xffff0000, v163
	v_pk_mul_f32 v[184:185], v[184:185], v[48:49] op_sel:[0,1] op_sel_hi:[1,1]
	v_pk_mul_f32 v[186:187], v[186:187], v[48:49] op_sel:[0,1] op_sel_hi:[1,1]
	v_pk_mul_f32 v[188:189], v[188:189], v[48:49] op_sel:[0,1] op_sel_hi:[1,1]
	v_pk_mul_f32 v[190:191], v[190:191], v[48:49] op_sel:[0,1] op_sel_hi:[1,1]
	v_pk_mul_f32 v[184:185], v[184:185], v[16:17]
	v_pk_mul_f32 v[186:187], v[186:187], v[18:19]
	v_pk_mul_f32 v[188:189], v[188:189], v[20:21]
	v_pk_mul_f32 v[190:191], v[190:191], v[22:23]
	v_cvt_pk_bf16_f32 v176, v184, v185
	v_cvt_pk_bf16_f32 v177, v186, v187
	v_cvt_pk_bf16_f32 v178, v188, v189
	v_cvt_pk_bf16_f32 v179, v190, v191
	global_store_dwordx4 v50, v[176:179], s[26:27] offset:2048
	v_lshlrev_b32_e32 v184, 16, v164
	v_and_b32_e32 v185, 0xffff0000, v164
	v_lshlrev_b32_e32 v186, 16, v165
	v_and_b32_e32 v187, 0xffff0000, v165
	v_lshlrev_b32_e32 v188, 16, v166
	v_and_b32_e32 v189, 0xffff0000, v166
	v_lshlrev_b32_e32 v190, 16, v167
	v_and_b32_e32 v191, 0xffff0000, v167
	v_pk_mul_f32 v[184:185], v[184:185], v[48:49] op_sel:[0,1] op_sel_hi:[1,1]
	v_pk_mul_f32 v[186:187], v[186:187], v[48:49] op_sel:[0,1] op_sel_hi:[1,1]
	v_pk_mul_f32 v[188:189], v[188:189], v[48:49] op_sel:[0,1] op_sel_hi:[1,1]
	v_pk_mul_f32 v[190:191], v[190:191], v[48:49] op_sel:[0,1] op_sel_hi:[1,1]
	v_pk_mul_f32 v[184:185], v[184:185], v[24:25]
	v_pk_mul_f32 v[186:187], v[186:187], v[26:27]
	v_pk_mul_f32 v[188:189], v[188:189], v[28:29]
	v_pk_mul_f32 v[190:191], v[190:191], v[30:31]
	v_cvt_pk_bf16_f32 v180, v184, v185
	v_cvt_pk_bf16_f32 v181, v186, v187
	v_cvt_pk_bf16_f32 v182, v188, v189
	v_cvt_pk_bf16_f32 v183, v190, v191
	global_store_dwordx4 v50, v[180:183], s[26:27] offset:3072
	s_cmp_lt_u32 s3, 2
	s_cbranch_scc0 .Lp4_nosample
	s_lshl_b32 s10, s2, 1
	s_add_u32 s10, s10, s3
	s_add_u32 s10, s10, 0x2000
	s_load_dwordx2 s[22:23], s[8:9], 0xd0
	s_lshl_b32 s17, s10, 13
	s_waitcnt lgkmcnt(0)
	s_add_u32 s14, s22, 0x1acd0000
	s_addc_u32 s15, s23, 0
	s_add_u32 s14, s14, s17
	s_addc_u32 s15, s15, 0
	s_mul_i32 s17, s10, 0x1800
	s_add_u32 s18, s22, 0x135d0000
	s_addc_u32 s19, s23, 0
	s_add_u32 s18, s18, s17
	s_addc_u32 s19, s19, 0
	s_mul_i32 s17, s10, 0x4a00
	s_add_u32 s20, s22, 0x9890000
	s_addc_u32 s21, s23, 0
	s_add_u32 s20, s20, s17
	s_addc_u32 s21, s21, 0
.Lp4_nosample:
	global_load_dwordx4 v[56:59], v50, s[14:15] offset:0
	global_load_dwordx4 v[60:63], v50, s[14:15] offset:1024
	global_load_dwordx4 v[64:67], v50, s[14:15] offset:2048
	global_load_dwordx4 v[68:71], v50, s[14:15] offset:3072
	global_load_dwordx4 v[72:75], v50, s[18:19] offset:0
	global_load_dwordx4 v[76:79], v50, s[18:19] offset:1024
	global_load_dwordx4 v[80:83], v50, s[18:19] offset:2048
	global_load_dwordx4 v[84:87], v50, s[18:19] offset:3072
	global_load_dwordx4 v[88:91], v50, s[20:21] offset:0
	global_load_dwordx4 v[92:95], v50, s[20:21] offset:1024
	global_load_dwordx4 v[96:99], v50, s[20:21] offset:2048
	global_load_dwordx4 v[100:103], v50, s[20:21] offset:3072
	s_mov_b32 s26, s14
	s_mov_b32 s27, s15
	s_waitcnt vmcnt(16)
; __device__ __forceinline__ float siluf_(float x) { return x * __builtin_amdgcn_rcpf(1.f + __expf(-x)); }
; __device__ __forceinline__ void mix_finalize_ssd(size_t row, bf16_t* MIX, const bf16_t* XBC, const bf16_t* PROJ, const float* d_skip, const float* ssd_norm_w, int lane, bf16_t* ssd_dst) {
;     ...
;         for (int k = 0; k < 4; ++k) { float f[8], xf[8], zf[8]; unpack8(yv[k], f); unpack8(xv[k], xf); unpack8(zv[k], zf);
; #pragma unroll
;             for (int e = 0; e < 8; ++e) { f[e] = (f[e] + dsk[k] * xf[e]) * siluf_(zf[e]); s += f[e] * f[e]; }
;             yv[k] = pack8(f); }
	v_mov_b32_e32 v44, 0
	v_mov_b32_e32 v45, 0
	v_lshlrev_b32_e32 v184, 16, v104
	v_and_b32_e32 v185, 0xffff0000, v104
	v_lshlrev_b32_e32 v186, 16, v105
	v_and_b32_e32 v187, 0xffff0000, v105
	v_lshlrev_b32_e32 v188, 16, v106
	v_and_b32_e32 v189, 0xffff0000, v106
	v_lshlrev_b32_e32 v190, 16, v107
	v_and_b32_e32 v191, 0xffff0000, v107
	v_lshlrev_b32_e32 v192, 16, v120
	v_and_b32_e32 v193, 0xffff0000, v120
	v_lshlrev_b32_e32 v194, 16, v121
	v_and_b32_e32 v195, 0xffff0000, v121
	v_lshlrev_b32_e32 v196, 16, v122
	v_and_b32_e32 v197, 0xffff0000, v122
	v_lshlrev_b32_e32 v198, 16, v123
	v_and_b32_e32 v199, 0xffff0000, v123
	v_lshlrev_b32_e32 v200, 16, v136
	v_and_b32_e32 v201, 0xffff0000, v136
	v_lshlrev_b32_e32 v202, 16, v137
	v_and_b32_e32 v203, 0xffff0000, v137
	v_lshlrev_b32_e32 v204, 16, v138
	v_and_b32_e32 v205, 0xffff0000, v138
	v_lshlrev_b32_e32 v206, 16, v139
	v_and_b32_e32 v207, 0xffff0000, v139
	v_pk_fma_f32 v[184:185], v[192:193], v[32:33], v[184:185] op_sel:[0,0,0] op_sel_hi:[1,0,1]
	v_pk_fma_f32 v[186:187], v[194:195], v[32:33], v[186:187] op_sel:[0,0,0] op_sel_hi:[1,0,1]
	v_pk_fma_f32 v[188:189], v[196:197], v[32:33], v[188:189] op_sel:[0,0,0] op_sel_hi:[1,0,1]
	v_pk_fma_f32 v[190:191], v[198:199], v[32:33], v[190:191] op_sel:[0,0,0] op_sel_hi:[1,0,1]
	v_pk_mul_f32 v[36:37], v[200:201], v[46:47] op_sel:[0,0] op_sel_hi:[1,0]
	v_pk_mul_f32 v[38:39], v[202:203], v[46:47] op_sel:[0,0] op_sel_hi:[1,0]
	v_pk_mul_f32 v[40:41], v[204:205], v[46:47] op_sel:[0,0] op_sel_hi:[1,0]
	v_pk_mul_f32 v[42:43], v[206:207], v[46:47] op_sel:[0,0] op_sel_hi:[1,0]
	v_exp_f32_e32 v36, v36
	v_exp_f32_e32 v37, v37
	v_exp_f32_e32 v38, v38
	v_exp_f32_e32 v39, v39
	v_exp_f32_e32 v40, v40
	v_exp_f32_e32 v41, v41
	v_exp_f32_e32 v42, v42
	v_exp_f32_e32 v43, v43
	v_pk_add_f32 v[36:37], v[36:37], v[46:47] op_sel:[0,1] op_sel_hi:[1,1]
	v_pk_add_f32 v[38:39], v[38:39], v[46:47] op_sel:[0,1] op_sel_hi:[1,1]
	v_pk_add_f32 v[40:41], v[40:41], v[46:47] op_sel:[0,1] op_sel_hi:[1,1]
	v_pk_add_f32 v[42:43], v[42:43], v[46:47] op_sel:[0,1] op_sel_hi:[1,1]
	v_rcp_f32_e32 v36, v36
	v_rcp_f32_e32 v37, v37
	v_rcp_f32_e32 v38, v38
	v_rcp_f32_e32 v39, v39
	v_rcp_f32_e32 v40, v40
	v_rcp_f32_e32 v41, v41
	v_rcp_f32_e32 v42, v42
	v_rcp_f32_e32 v43, v43
	v_pk_mul_f32 v[36:37], v[200:201], v[36:37]
	v_pk_mul_f32 v[38:39], v[202:203], v[38:39]
	v_pk_mul_f32 v[40:41], v[204:205], v[40:41]
	v_pk_mul_f32 v[42:43], v[206:207], v[42:43]
	v_pk_mul_f32 v[184:185], v[184:185], v[36:37]
	v_pk_mul_f32 v[186:187], v[186:187], v[38:39]
	v_pk_mul_f32 v[188:189], v[188:189], v[40:41]
	v_pk_mul_f32 v[190:191], v[190:191], v[42:43]
	v_pk_fma_f32 v[44:45], v[184:185], v[184:185], v[44:45]
	v_pk_fma_f32 v[44:45], v[186:187], v[186:187], v[44:45]
	v_pk_fma_f32 v[44:45], v[188:189], v[188:189], v[44:45]
	v_pk_fma_f32 v[44:45], v[190:191], v[190:191], v[44:45]
	v_cvt_pk_bf16_f32 v152, v184, v185
	v_cvt_pk_bf16_f32 v153, v186, v187
	v_cvt_pk_bf16_f32 v154, v188, v189
	v_cvt_pk_bf16_f32 v155, v190, v191
	v_lshlrev_b32_e32 v184, 16, v108
	v_and_b32_e32 v185, 0xffff0000, v108
	v_lshlrev_b32_e32 v186, 16, v109
	v_and_b32_e32 v187, 0xffff0000, v109
	v_lshlrev_b32_e32 v188, 16, v110
	v_and_b32_e32 v189, 0xffff0000, v110
	v_lshlrev_b32_e32 v190, 16, v111
	v_and_b32_e32 v191, 0xffff0000, v111
	v_lshlrev_b32_e32 v192, 16, v124
	v_and_b32_e32 v193, 0xffff0000, v124
	v_lshlrev_b32_e32 v194, 16, v125
	v_and_b32_e32 v195, 0xffff0000, v125
	v_lshlrev_b32_e32 v196, 16, v126
	v_and_b32_e32 v197, 0xffff0000, v126
	v_lshlrev_b32_e32 v198, 16, v127
	v_and_b32_e32 v199, 0xffff0000, v127
	v_lshlrev_b32_e32 v200, 16, v140
	v_and_b32_e32 v201, 0xffff0000, v140
	v_lshlrev_b32_e32 v202, 16, v141
	v_and_b32_e32 v203, 0xffff0000, v141
	v_lshlrev_b32_e32 v204, 16, v142
	v_and_b32_e32 v205, 0xffff0000, v142
	v_lshlrev_b32_e32 v206, 16, v143
	v_and_b32_e32 v207, 0xffff0000, v143
	v_pk_fma_f32 v[184:185], v[192:193], v[32:33], v[184:185] op_sel:[0,1,0] op_sel_hi:[1,1,1]
	v_pk_fma_f32 v[186:187], v[194:195], v[32:33], v[186:187] op_sel:[0,1,0] op_sel_hi:[1,1,1]
	v_pk_fma_f32 v[188:189], v[196:197], v[32:33], v[188:189] op_sel:[0,1,0] op_sel_hi:[1,1,1]
	v_pk_fma_f32 v[190:191], v[198:199], v[32:33], v[190:191] op_sel:[0,1,0] op_sel_hi:[1,1,1]
	v_pk_mul_f32 v[36:37], v[200:201], v[46:47] op_sel:[0,0] op_sel_hi:[1,0]
	v_pk_mul_f32 v[38:39], v[202:203], v[46:47] op_sel:[0,0] op_sel_hi:[1,0]
	v_pk_mul_f32 v[40:41], v[204:205], v[46:47] op_sel:[0,0] op_sel_hi:[1,0]
	v_pk_mul_f32 v[42:43], v[206:207], v[46:47] op_sel:[0,0] op_sel_hi:[1,0]
	v_exp_f32_e32 v36, v36
	v_exp_f32_e32 v37, v37
	v_exp_f32_e32 v38, v38
	v_exp_f32_e32 v39, v39
	v_exp_f32_e32 v40, v40
	v_exp_f32_e32 v41, v41
	v_exp_f32_e32 v42, v42
	v_exp_f32_e32 v43, v43
	v_pk_add_f32 v[36:37], v[36:37], v[46:47] op_sel:[0,1] op_sel_hi:[1,1]
	v_pk_add_f32 v[38:39], v[38:39], v[46:47] op_sel:[0,1] op_sel_hi:[1,1]
	v_pk_add_f32 v[40:41], v[40:41], v[46:47] op_sel:[0,1] op_sel_hi:[1,1]
	v_pk_add_f32 v[42:43], v[42:43], v[46:47] op_sel:[0,1] op_sel_hi:[1,1]
	v_rcp_f32_e32 v36, v36
	v_rcp_f32_e32 v37, v37
	v_rcp_f32_e32 v38, v38
	v_rcp_f32_e32 v39, v39
	v_rcp_f32_e32 v40, v40
	v_rcp_f32_e32 v41, v41
	v_rcp_f32_e32 v42, v42
	v_rcp_f32_e32 v43, v43
	v_pk_mul_f32 v[36:37], v[200:201], v[36:37]
	v_pk_mul_f32 v[38:39], v[202:203], v[38:39]
	v_pk_mul_f32 v[40:41], v[204:205], v[40:41]
	v_pk_mul_f32 v[42:43], v[206:207], v[42:43]
	v_pk_mul_f32 v[184:185], v[184:185], v[36:37]
	v_pk_mul_f32 v[186:187], v[186:187], v[38:39]
	v_pk_mul_f32 v[188:189], v[188:189], v[40:41]
	v_pk_mul_f32 v[190:191], v[190:191], v[42:43]
	v_pk_fma_f32 v[44:45], v[184:185], v[184:185], v[44:45]
	v_pk_fma_f32 v[44:45], v[186:187], v[186:187], v[44:45]
; __device__ __forceinline__ float siluf_(float x) { return x * __builtin_amdgcn_rcpf(1.f + __expf(-x)); }
; __device__ __forceinline__ void mix_finalize_ssd(size_t row, bf16_t* MIX, const bf16_t* XBC, const bf16_t* PROJ, const float* d_skip, const float* ssd_norm_w, int lane, bf16_t* ssd_dst) {
;     ...
;         for (int k = 0; k < 4; ++k) { float f[8], xf[8], zf[8]; unpack8(yv[k], f); unpack8(xv[k], xf); unpack8(zv[k], zf);
; #pragma unroll
;             for (int e = 0; e < 8; ++e) { f[e] = (f[e] + dsk[k] * xf[e]) * siluf_(zf[e]); s += f[e] * f[e]; }
;             yv[k] = pack8(f); }
	v_pk_fma_f32 v[44:45], v[188:189], v[188:189], v[44:45]
	v_pk_fma_f32 v[44:45], v[190:191], v[190:191], v[44:45]
	v_cvt_pk_bf16_f32 v156, v184, v185
	v_cvt_pk_bf16_f32 v157, v186, v187
	v_cvt_pk_bf16_f32 v158, v188, v189
	v_cvt_pk_bf16_f32 v159, v190, v191
	v_lshlrev_b32_e32 v184, 16, v112
	v_and_b32_e32 v185, 0xffff0000, v112
	v_lshlrev_b32_e32 v186, 16, v113
	v_and_b32_e32 v187, 0xffff0000, v113
	v_lshlrev_b32_e32 v188, 16, v114
	v_and_b32_e32 v189, 0xffff0000, v114
	v_lshlrev_b32_e32 v190, 16, v115
	v_and_b32_e32 v191, 0xffff0000, v115
	v_lshlrev_b32_e32 v192, 16, v128
	v_and_b32_e32 v193, 0xffff0000, v128
	v_lshlrev_b32_e32 v194, 16, v129
	v_and_b32_e32 v195, 0xffff0000, v129
	v_lshlrev_b32_e32 v196, 16, v130
	v_and_b32_e32 v197, 0xffff0000, v130
	v_lshlrev_b32_e32 v198, 16, v131
	v_and_b32_e32 v199, 0xffff0000, v131
	v_lshlrev_b32_e32 v200, 16, v144
	v_and_b32_e32 v201, 0xffff0000, v144
	v_lshlrev_b32_e32 v202, 16, v145
	v_and_b32_e32 v203, 0xffff0000, v145
	v_lshlrev_b32_e32 v204, 16, v146
	v_and_b32_e32 v205, 0xffff0000, v146
	v_lshlrev_b32_e32 v206, 16, v147
	v_and_b32_e32 v207, 0xffff0000, v147
	v_pk_fma_f32 v[184:185], v[192:193], v[34:35], v[184:185] op_sel:[0,0,0] op_sel_hi:[1,0,1]
	v_pk_fma_f32 v[186:187], v[194:195], v[34:35], v[186:187] op_sel:[0,0,0] op_sel_hi:[1,0,1]
	v_pk_fma_f32 v[188:189], v[196:197], v[34:35], v[188:189] op_sel:[0,0,0] op_sel_hi:[1,0,1]
	v_pk_fma_f32 v[190:191], v[198:199], v[34:35], v[190:191] op_sel:[0,0,0] op_sel_hi:[1,0,1]
	v_pk_mul_f32 v[36:37], v[200:201], v[46:47] op_sel:[0,0] op_sel_hi:[1,0]
	v_pk_mul_f32 v[38:39], v[202:203], v[46:47] op_sel:[0,0] op_sel_hi:[1,0]
	v_pk_mul_f32 v[40:41], v[204:205], v[46:47] op_sel:[0,0] op_sel_hi:[1,0]
	v_pk_mul_f32 v[42:43], v[206:207], v[46:47] op_sel:[0,0] op_sel_hi:[1,0]
	v_exp_f32_e32 v36, v36
	v_exp_f32_e32 v37, v37
	v_exp_f32_e32 v38, v38
	v_exp_f32_e32 v39, v39
	v_exp_f32_e32 v40, v40
	v_exp_f32_e32 v41, v41
	v_exp_f32_e32 v42, v42
	v_exp_f32_e32 v43, v43
	v_pk_add_f32 v[36:37], v[36:37], v[46:47] op_sel:[0,1] op_sel_hi:[1,1]
	v_pk_add_f32 v[38:39], v[38:39], v[46:47] op_sel:[0,1] op_sel_hi:[1,1]
	v_pk_add_f32 v[40:41], v[40:41], v[46:47] op_sel:[0,1] op_sel_hi:[1,1]
	v_pk_add_f32 v[42:43], v[42:43], v[46:47] op_sel:[0,1] op_sel_hi:[1,1]
	v_rcp_f32_e32 v36, v36
	v_rcp_f32_e32 v37, v37
	v_rcp_f32_e32 v38, v38
	v_rcp_f32_e32 v39, v39
	v_rcp_f32_e32 v40, v40
	v_rcp_f32_e32 v41, v41
	v_rcp_f32_e32 v42, v42
	v_rcp_f32_e32 v43, v43
	v_pk_mul_f32 v[36:37], v[200:201], v[36:37]
	v_pk_mul_f32 v[38:39], v[202:203], v[38:39]
	v_pk_mul_f32 v[40:41], v[204:205], v[40:41]
	v_pk_mul_f32 v[42:43], v[206:207], v[42:43]
	v_pk_mul_f32 v[184:185], v[184:185], v[36:37]
	v_pk_mul_f32 v[186:187], v[186:187], v[38:39]
	v_pk_mul_f32 v[188:189], v[188:189], v[40:41]
	v_pk_mul_f32 v[190:191], v[190:191], v[42:43]
	v_pk_fma_f32 v[44:45], v[184:185], v[184:185], v[44:45]
	v_pk_fma_f32 v[44:45], v[186:187], v[186:187], v[44:45]
	v_pk_fma_f32 v[44:45], v[188:189], v[188:189], v[44:45]
	v_pk_fma_f32 v[44:45], v[190:191], v[190:191], v[44:45]
	v_cvt_pk_bf16_f32 v160, v184, v185
	v_cvt_pk_bf16_f32 v161, v186, v187
	v_cvt_pk_bf16_f32 v162, v188, v189
	v_cvt_pk_bf16_f32 v163, v190, v191
	v_lshlrev_b32_e32 v184, 16, v116
	v_and_b32_e32 v185, 0xffff0000, v116
	v_lshlrev_b32_e32 v186, 16, v117
	v_and_b32_e32 v187, 0xffff0000, v117
	v_lshlrev_b32_e32 v188, 16, v118
	v_and_b32_e32 v189, 0xffff0000, v118
	v_lshlrev_b32_e32 v190, 16, v119
	v_and_b32_e32 v191, 0xffff0000, v119
	v_lshlrev_b32_e32 v192, 16, v132
	v_and_b32_e32 v193, 0xffff0000, v132
	v_lshlrev_b32_e32 v194, 16, v133
	v_and_b32_e32 v195, 0xffff0000, v133
	v_lshlrev_b32_e32 v196, 16, v134
	v_and_b32_e32 v197, 0xffff0000, v134
	v_lshlrev_b32_e32 v198, 16, v135
	v_and_b32_e32 v199, 0xffff0000, v135
	v_lshlrev_b32_e32 v200, 16, v148
	v_and_b32_e32 v201, 0xffff0000, v148
	v_lshlrev_b32_e32 v202, 16, v149
	v_and_b32_e32 v203, 0xffff0000, v149
	v_lshlrev_b32_e32 v204, 16, v150
	v_and_b32_e32 v205, 0xffff0000, v150
	v_lshlrev_b32_e32 v206, 16, v151
	v_and_b32_e32 v207, 0xffff0000, v151
	v_pk_fma_f32 v[184:185], v[192:193], v[34:35], v[184:185] op_sel:[0,1,0] op_sel_hi:[1,1,1]
	v_pk_fma_f32 v[186:187], v[194:195], v[34:35], v[186:187] op_sel:[0,1,0] op_sel_hi:[1,1,1]
	v_pk_fma_f32 v[188:189], v[196:197], v[34:35], v[188:189] op_sel:[0,1,0] op_sel_hi:[1,1,1]
	v_pk_fma_f32 v[190:191], v[198:199], v[34:35], v[190:191] op_sel:[0,1,0] op_sel_hi:[1,1,1]
	v_pk_mul_f32 v[36:37], v[200:201], v[46:47] op_sel:[0,0] op_sel_hi:[1,0]
	v_pk_mul_f32 v[38:39], v[202:203], v[46:47] op_sel:[0,0] op_sel_hi:[1,0]
	v_pk_mul_f32 v[40:41], v[204:205], v[46:47] op_sel:[0,0] op_sel_hi:[1,0]
	v_pk_mul_f32 v[42:43], v[206:207], v[46:47] op_sel:[0,0] op_sel_hi:[1,0]
	v_exp_f32_e32 v36, v36
	v_exp_f32_e32 v37, v37
	v_exp_f32_e32 v38, v38
	v_exp_f32_e32 v39, v39
	v_exp_f32_e32 v40, v40
	v_exp_f32_e32 v41, v41
	v_exp_f32_e32 v42, v42
	v_exp_f32_e32 v43, v43
	v_pk_add_f32 v[36:37], v[36:37], v[46:47] op_sel:[0,1] op_sel_hi:[1,1]
	v_pk_add_f32 v[38:39], v[38:39], v[46:47] op_sel:[0,1] op_sel_hi:[1,1]
	v_pk_add_f32 v[40:41], v[40:41], v[46:47] op_sel:[0,1] op_sel_hi:[1,1]
	v_pk_add_f32 v[42:43], v[42:43], v[46:47] op_sel:[0,1] op_sel_hi:[1,1]
	v_rcp_f32_e32 v36, v36
	v_rcp_f32_e32 v37, v37
	v_rcp_f32_e32 v38, v38
	v_rcp_f32_e32 v39, v39
	v_rcp_f32_e32 v40, v40
	v_rcp_f32_e32 v41, v41
	v_rcp_f32_e32 v42, v42
	v_rcp_f32_e32 v43, v43
	v_pk_mul_f32 v[36:37], v[200:201], v[36:37]
	v_pk_mul_f32 v[38:39], v[202:203], v[38:39]
	v_pk_mul_f32 v[40:41], v[204:205], v[40:41]
	v_pk_mul_f32 v[42:43], v[206:207], v[42:43]
	v_pk_mul_f32 v[184:185], v[184:185], v[36:37]
; __device__ __forceinline__ float siluf_(float x) { return x * __builtin_amdgcn_rcpf(1.f + __expf(-x)); }
; __device__ __forceinline__ void mix_finalize_ssd(size_t row, bf16_t* MIX, const bf16_t* XBC, const bf16_t* PROJ, const float* d_skip, const float* ssd_norm_w, int lane, bf16_t* ssd_dst) {
;     ...
;         for (int k = 0; k < 4; ++k) { float f[8], xf[8], zf[8]; unpack8(yv[k], f); unpack8(xv[k], xf); unpack8(zv[k], zf);
; #pragma unroll
;             for (int e = 0; e < 8; ++e) { f[e] = (f[e] + dsk[k] * xf[e]) * siluf_(zf[e]); s += f[e] * f[e]; }
;             yv[k] = pack8(f); }
;         const float r = rsqrtf(wave_sum(s) * (1.f / DM) + EPS);
; #pragma unroll 1
;         for (int k = 0; k < 4; ++k) { const int c = (k * 64 + lane) * 8;
;             const f32x4 w0 = *(const f32x4*)(ssd_norm_w + c), w1 = *(const f32x4*)(ssd_norm_w + c + 4);
;             const u32x4 yk = (k == 0) ? yv[0] : (k == 1) ? yv[1] : (k == 2) ? yv[2] : yv[3];
;             float f[8]; unpack8(yk, f);
;             float o[8]; o[0] = f[0] * r * w0.x; o[1] = f[1] * r * w0.y; o[2] = f[2] * r * w0.z; o[3] = f[3] * r * w0.w;
;             o[4] = f[4] * r * w1.x; o[5] = f[5] * r * w1.y; o[6] = f[6] * r * w1.z; o[7] = f[7] * r * w1.w;
;             *(u32x4*)(ssd_dst + c) = pack8(o); }
	v_pk_mul_f32 v[186:187], v[186:187], v[38:39]
	v_pk_mul_f32 v[188:189], v[188:189], v[40:41]
	v_pk_mul_f32 v[190:191], v[190:191], v[42:43]
	v_pk_fma_f32 v[44:45], v[184:185], v[184:185], v[44:45]
	v_pk_fma_f32 v[44:45], v[186:187], v[186:187], v[44:45]
	v_pk_fma_f32 v[44:45], v[188:189], v[188:189], v[44:45]
	v_pk_fma_f32 v[44:45], v[190:191], v[190:191], v[44:45]
	v_cvt_pk_bf16_f32 v164, v184, v185
	v_cvt_pk_bf16_f32 v165, v186, v187
	v_cvt_pk_bf16_f32 v166, v188, v189
	v_cvt_pk_bf16_f32 v167, v190, v191
	v_add_f32_e32 v208, v44, v45
	s_nop 1
	v_add_f32_dpp v209, v208, v208 quad_perm:[1,0,3,2] row_mask:0xf bank_mask:0xf
	s_nop 1
	v_add_f32_dpp v208, v209, v209 quad_perm:[2,3,0,1] row_mask:0xf bank_mask:0xf
	s_nop 1
	v_add_f32_dpp v209, v208, v208 row_half_mirror row_mask:0xf bank_mask:0xf
	s_nop 1
	v_add_f32_dpp v208, v209, v209 row_mirror row_mask:0xf bank_mask:0xf
	s_nop 1
	v_readlane_b32 s10, v208, 0
	v_readlane_b32 s11, v208, 16
	v_readlane_b32 s17, v208, 32
	v_readlane_b32 s24, v208, 48
	s_nop 3
	v_mov_b32_e32 v208, s10
	v_add_f32_e32 v208, s11, v208
	v_add_f32_e32 v208, s17, v208
	v_add_f32_e32 v208, s24, v208
	v_fmamk_f32 v208, v208, 0x3a000000, v48
	v_rsq_f32_e32 v49, v208
	s_nop 0
	v_lshlrev_b32_e32 v184, 16, v152
	v_and_b32_e32 v185, 0xffff0000, v152
	v_lshlrev_b32_e32 v186, 16, v153
	v_and_b32_e32 v187, 0xffff0000, v153
	v_lshlrev_b32_e32 v188, 16, v154
	v_and_b32_e32 v189, 0xffff0000, v154
	v_lshlrev_b32_e32 v190, 16, v155
	v_and_b32_e32 v191, 0xffff0000, v155
	v_pk_mul_f32 v[184:185], v[184:185], v[48:49] op_sel:[0,1] op_sel_hi:[1,1]
	v_pk_mul_f32 v[186:187], v[186:187], v[48:49] op_sel:[0,1] op_sel_hi:[1,1]
	v_pk_mul_f32 v[188:189], v[188:189], v[48:49] op_sel:[0,1] op_sel_hi:[1,1]
	v_pk_mul_f32 v[190:191], v[190:191], v[48:49] op_sel:[0,1] op_sel_hi:[1,1]
	v_pk_mul_f32 v[184:185], v[184:185], v[0:1]
	v_pk_mul_f32 v[186:187], v[186:187], v[2:3]
	v_pk_mul_f32 v[188:189], v[188:189], v[4:5]
	v_pk_mul_f32 v[190:191], v[190:191], v[6:7]
	v_cvt_pk_bf16_f32 v168, v184, v185
	v_cvt_pk_bf16_f32 v169, v186, v187
	v_cvt_pk_bf16_f32 v170, v188, v189
	v_cvt_pk_bf16_f32 v171, v190, v191
	global_store_dwordx4 v50, v[168:171], s[12:13] offset:0
	v_lshlrev_b32_e32 v184, 16, v156
	v_and_b32_e32 v185, 0xffff0000, v156
	v_lshlrev_b32_e32 v186, 16, v157
	v_and_b32_e32 v187, 0xffff0000, v157
	v_lshlrev_b32_e32 v188, 16, v158
	v_and_b32_e32 v189, 0xffff0000, v158
	v_lshlrev_b32_e32 v190, 16, v159
	v_and_b32_e32 v191, 0xffff0000, v159
	v_pk_mul_f32 v[184:185], v[184:185], v[48:49] op_sel:[0,1] op_sel_hi:[1,1]
	v_pk_mul_f32 v[186:187], v[186:187], v[48:49] op_sel:[0,1] op_sel_hi:[1,1]
	v_pk_mul_f32 v[188:189], v[188:189], v[48:49] op_sel:[0,1] op_sel_hi:[1,1]
	v_pk_mul_f32 v[190:191], v[190:191], v[48:49] op_sel:[0,1] op_sel_hi:[1,1]
	v_pk_mul_f32 v[184:185], v[184:185], v[8:9]
	v_pk_mul_f32 v[186:187], v[186:187], v[10:11]
	v_pk_mul_f32 v[188:189], v[188:189], v[12:13]
	v_pk_mul_f32 v[190:191], v[190:191], v[14:15]
	v_cvt_pk_bf16_f32 v172, v184, v185
	v_cvt_pk_bf16_f32 v173, v186, v187
	v_cvt_pk_bf16_f32 v174, v188, v189
	v_cvt_pk_bf16_f32 v175, v190, v191
	global_store_dwordx4 v50, v[172:175], s[12:13] offset:1024
	v_lshlrev_b32_e32 v184, 16, v160
	v_and_b32_e32 v185, 0xffff0000, v160
	v_lshlrev_b32_e32 v186, 16, v161
	v_and_b32_e32 v187, 0xffff0000, v161
	v_lshlrev_b32_e32 v188, 16, v162
	v_and_b32_e32 v189, 0xffff0000, v162
	v_lshlrev_b32_e32 v190, 16, v163
	v_and_b32_e32 v191, 0xffff0000, v163
	v_pk_mul_f32 v[184:185], v[184:185], v[48:49] op_sel:[0,1] op_sel_hi:[1,1]
	v_pk_mul_f32 v[186:187], v[186:187], v[48:49] op_sel:[0,1] op_sel_hi:[1,1]
	v_pk_mul_f32 v[188:189], v[188:189], v[48:49] op_sel:[0,1] op_sel_hi:[1,1]
	v_pk_mul_f32 v[190:191], v[190:191], v[48:49] op_sel:[0,1] op_sel_hi:[1,1]
	v_pk_mul_f32 v[184:185], v[184:185], v[16:17]
	v_pk_mul_f32 v[186:187], v[186:187], v[18:19]
	v_pk_mul_f32 v[188:189], v[188:189], v[20:21]
	v_pk_mul_f32 v[190:191], v[190:191], v[22:23]
	v_cvt_pk_bf16_f32 v176, v184, v185
	v_cvt_pk_bf16_f32 v177, v186, v187
	v_cvt_pk_bf16_f32 v178, v188, v189
	v_cvt_pk_bf16_f32 v179, v190, v191
	global_store_dwordx4 v50, v[176:179], s[12:13] offset:2048
	v_lshlrev_b32_e32 v184, 16, v164
	v_and_b32_e32 v185, 0xffff0000, v164
	v_lshlrev_b32_e32 v186, 16, v165
	v_and_b32_e32 v187, 0xffff0000, v165
	v_lshlrev_b32_e32 v188, 16, v166
	v_and_b32_e32 v189, 0xffff0000, v166
	v_lshlrev_b32_e32 v190, 16, v167
	v_and_b32_e32 v191, 0xffff0000, v167
	v_pk_mul_f32 v[184:185], v[184:185], v[48:49] op_sel:[0,1] op_sel_hi:[1,1]
	v_pk_mul_f32 v[186:187], v[186:187], v[48:49] op_sel:[0,1] op_sel_hi:[1,1]
	v_pk_mul_f32 v[188:189], v[188:189], v[48:49] op_sel:[0,1] op_sel_hi:[1,1]
	v_pk_mul_f32 v[190:191], v[190:191], v[48:49] op_sel:[0,1] op_sel_hi:[1,1]
	v_pk_mul_f32 v[184:185], v[184:185], v[24:25]
	v_pk_mul_f32 v[186:187], v[186:187], v[26:27]
	v_pk_mul_f32 v[188:189], v[188:189], v[28:29]
	v_pk_mul_f32 v[190:191], v[190:191], v[30:31]
	v_cvt_pk_bf16_f32 v180, v184, v185
	v_cvt_pk_bf16_f32 v181, v186, v187
	v_cvt_pk_bf16_f32 v182, v188, v189
	v_cvt_pk_bf16_f32 v183, v190, v191
	global_store_dwordx4 v50, v[180:183], s[12:13] offset:3072
	s_cmp_lt_u32 s3, 2
	s_cbranch_scc0 .LBB0_561
; __device__ __forceinline__ float siluf_(float x) { return x * __builtin_amdgcn_rcpf(1.f + __expf(-x)); }
; __device__ __forceinline__ void mix_finalize_ssd(size_t row, bf16_t* MIX, const bf16_t* XBC, const bf16_t* PROJ, const float* d_skip, const float* ssd_norm_w, int lane, bf16_t* ssd_dst) {
;     ...
;         for (int k = 0; k < 4; ++k) { float f[8], xf[8], zf[8]; unpack8(yv[k], f); unpack8(xv[k], xf); unpack8(zv[k], zf);
; #pragma unroll
;             for (int e = 0; e < 8; ++e) { f[e] = (f[e] + dsk[k] * xf[e]) * siluf_(zf[e]); s += f[e] * f[e]; }
;             yv[k] = pack8(f); }
; __global__ void __launch_bounds__(512, 2) mk_fwd(Args args) {
;     ...
;             const u32x4 yv = *(const u32x4*)(mp + c), xv = *(const u32x4*)(XBC + m * XBCW + c), zv = *(const u32x4*)(PROJ + m * NPROJ + CZ + c);
;             const float dsk = d_skip[c >> 6]; const f32x4 w0 = *(const f32x4*)(ssd_norm_w + c), w1 = *(const f32x4*)(ssd_norm_w + c + 4);
;             float f[8], xf[8], zf[8]; unpack8(yv, f); unpack8(xv, xf); unpack8(zv, zf);
;             float sq = 0.f;
; #pragma unroll
;             for (int e = 0; e < 8; ++e) { f[e] = (f[e] + dsk * xf[e]) * siluf_(zf[e]); sq += f[e] * f[e]; }
	s_waitcnt vmcnt(4)
	v_mov_b32_e32 v44, 0
	v_mov_b32_e32 v45, 0
	v_lshlrev_b32_e32 v184, 16, v56
	v_and_b32_e32 v185, 0xffff0000, v56
	v_lshlrev_b32_e32 v186, 16, v57
	v_and_b32_e32 v187, 0xffff0000, v57
	v_lshlrev_b32_e32 v188, 16, v58
	v_and_b32_e32 v189, 0xffff0000, v58
	v_lshlrev_b32_e32 v190, 16, v59
	v_and_b32_e32 v191, 0xffff0000, v59
	v_lshlrev_b32_e32 v192, 16, v72
	v_and_b32_e32 v193, 0xffff0000, v72
	v_lshlrev_b32_e32 v194, 16, v73
	v_and_b32_e32 v195, 0xffff0000, v73
	v_lshlrev_b32_e32 v196, 16, v74
	v_and_b32_e32 v197, 0xffff0000, v74
	v_lshlrev_b32_e32 v198, 16, v75
	v_and_b32_e32 v199, 0xffff0000, v75
	v_lshlrev_b32_e32 v200, 16, v88
	v_and_b32_e32 v201, 0xffff0000, v88
	v_lshlrev_b32_e32 v202, 16, v89
	v_and_b32_e32 v203, 0xffff0000, v89
	v_lshlrev_b32_e32 v204, 16, v90
	v_and_b32_e32 v205, 0xffff0000, v90
	v_lshlrev_b32_e32 v206, 16, v91
	v_and_b32_e32 v207, 0xffff0000, v91
	v_pk_fma_f32 v[184:185], v[192:193], v[32:33], v[184:185] op_sel:[0,0,0] op_sel_hi:[1,0,1]
	v_pk_fma_f32 v[186:187], v[194:195], v[32:33], v[186:187] op_sel:[0,0,0] op_sel_hi:[1,0,1]
	v_pk_fma_f32 v[188:189], v[196:197], v[32:33], v[188:189] op_sel:[0,0,0] op_sel_hi:[1,0,1]
	v_pk_fma_f32 v[190:191], v[198:199], v[32:33], v[190:191] op_sel:[0,0,0] op_sel_hi:[1,0,1]
	v_pk_mul_f32 v[36:37], v[200:201], v[46:47] op_sel:[0,0] op_sel_hi:[1,0]
	v_pk_mul_f32 v[38:39], v[202:203], v[46:47] op_sel:[0,0] op_sel_hi:[1,0]
	v_pk_mul_f32 v[40:41], v[204:205], v[46:47] op_sel:[0,0] op_sel_hi:[1,0]
	v_pk_mul_f32 v[42:43], v[206:207], v[46:47] op_sel:[0,0] op_sel_hi:[1,0]
	v_exp_f32_e32 v36, v36
	v_exp_f32_e32 v37, v37
	v_exp_f32_e32 v38, v38
	v_exp_f32_e32 v39, v39
	v_exp_f32_e32 v40, v40
	v_exp_f32_e32 v41, v41
	v_exp_f32_e32 v42, v42
	v_exp_f32_e32 v43, v43
	v_pk_add_f32 v[36:37], v[36:37], v[46:47] op_sel:[0,1] op_sel_hi:[1,1]
	v_pk_add_f32 v[38:39], v[38:39], v[46:47] op_sel:[0,1] op_sel_hi:[1,1]
	v_pk_add_f32 v[40:41], v[40:41], v[46:47] op_sel:[0,1] op_sel_hi:[1,1]
	v_pk_add_f32 v[42:43], v[42:43], v[46:47] op_sel:[0,1] op_sel_hi:[1,1]
	v_rcp_f32_e32 v36, v36
	v_rcp_f32_e32 v37, v37
	v_rcp_f32_e32 v38, v38
	v_rcp_f32_e32 v39, v39
	v_rcp_f32_e32 v40, v40
	v_rcp_f32_e32 v41, v41
	v_rcp_f32_e32 v42, v42
	v_rcp_f32_e32 v43, v43
	v_pk_mul_f32 v[36:37], v[200:201], v[36:37]
	v_pk_mul_f32 v[38:39], v[202:203], v[38:39]
	v_pk_mul_f32 v[40:41], v[204:205], v[40:41]
	v_pk_mul_f32 v[42:43], v[206:207], v[42:43]
	v_pk_mul_f32 v[184:185], v[184:185], v[36:37]
	v_pk_mul_f32 v[186:187], v[186:187], v[38:39]
	v_pk_mul_f32 v[188:189], v[188:189], v[40:41]
	v_pk_mul_f32 v[190:191], v[190:191], v[42:43]
	v_pk_fma_f32 v[44:45], v[184:185], v[184:185], v[44:45]
	v_pk_fma_f32 v[44:45], v[186:187], v[186:187], v[44:45]
	v_pk_fma_f32 v[44:45], v[188:189], v[188:189], v[44:45]
	v_pk_fma_f32 v[44:45], v[190:191], v[190:191], v[44:45]
	v_cvt_pk_bf16_f32 v152, v184, v185
	v_cvt_pk_bf16_f32 v153, v186, v187
	v_cvt_pk_bf16_f32 v154, v188, v189
	v_cvt_pk_bf16_f32 v155, v190, v191
	v_lshlrev_b32_e32 v184, 16, v60
	v_and_b32_e32 v185, 0xffff0000, v60
	v_lshlrev_b32_e32 v186, 16, v61
	v_and_b32_e32 v187, 0xffff0000, v61
	v_lshlrev_b32_e32 v188, 16, v62
	v_and_b32_e32 v189, 0xffff0000, v62
	v_lshlrev_b32_e32 v190, 16, v63
	v_and_b32_e32 v191, 0xffff0000, v63
	v_lshlrev_b32_e32 v192, 16, v76
	v_and_b32_e32 v193, 0xffff0000, v76
	v_lshlrev_b32_e32 v194, 16, v77
	v_and_b32_e32 v195, 0xffff0000, v77
	v_lshlrev_b32_e32 v196, 16, v78
	v_and_b32_e32 v197, 0xffff0000, v78
	v_lshlrev_b32_e32 v198, 16, v79
	v_and_b32_e32 v199, 0xffff0000, v79
	v_lshlrev_b32_e32 v200, 16, v92
	v_and_b32_e32 v201, 0xffff0000, v92
	v_lshlrev_b32_e32 v202, 16, v93
	v_and_b32_e32 v203, 0xffff0000, v93
	v_lshlrev_b32_e32 v204, 16, v94
	v_and_b32_e32 v205, 0xffff0000, v94
	v_lshlrev_b32_e32 v206, 16, v95
	v_and_b32_e32 v207, 0xffff0000, v95
	v_pk_fma_f32 v[184:185], v[192:193], v[32:33], v[184:185] op_sel:[0,1,0] op_sel_hi:[1,1,1]
	v_pk_fma_f32 v[186:187], v[194:195], v[32:33], v[186:187] op_sel:[0,1,0] op_sel_hi:[1,1,1]
	v_pk_fma_f32 v[188:189], v[196:197], v[32:33], v[188:189] op_sel:[0,1,0] op_sel_hi:[1,1,1]
	v_pk_fma_f32 v[190:191], v[198:199], v[32:33], v[190:191] op_sel:[0,1,0] op_sel_hi:[1,1,1]
	v_pk_mul_f32 v[36:37], v[200:201], v[46:47] op_sel:[0,0] op_sel_hi:[1,0]
	v_pk_mul_f32 v[38:39], v[202:203], v[46:47] op_sel:[0,0] op_sel_hi:[1,0]
	v_pk_mul_f32 v[40:41], v[204:205], v[46:47] op_sel:[0,0] op_sel_hi:[1,0]
	v_pk_mul_f32 v[42:43], v[206:207], v[46:47] op_sel:[0,0] op_sel_hi:[1,0]
	v_exp_f32_e32 v36, v36
	v_exp_f32_e32 v37, v37
	v_exp_f32_e32 v38, v38
	v_exp_f32_e32 v39, v39
	v_exp_f32_e32 v40, v40
	v_exp_f32_e32 v41, v41
	v_exp_f32_e32 v42, v42
	v_exp_f32_e32 v43, v43
	v_pk_add_f32 v[36:37], v[36:37], v[46:47] op_sel:[0,1] op_sel_hi:[1,1]
	v_pk_add_f32 v[38:39], v[38:39], v[46:47] op_sel:[0,1] op_sel_hi:[1,1]
	v_pk_add_f32 v[40:41], v[40:41], v[46:47] op_sel:[0,1] op_sel_hi:[1,1]
	v_pk_add_f32 v[42:43], v[42:43], v[46:47] op_sel:[0,1] op_sel_hi:[1,1]
	v_rcp_f32_e32 v36, v36
	v_rcp_f32_e32 v37, v37
	v_rcp_f32_e32 v38, v38
	v_rcp_f32_e32 v39, v39
	v_rcp_f32_e32 v40, v40
	v_rcp_f32_e32 v41, v41
	v_rcp_f32_e32 v42, v42
	v_rcp_f32_e32 v43, v43
	v_pk_mul_f32 v[36:37], v[200:201], v[36:37]
	v_pk_mul_f32 v[38:39], v[202:203], v[38:39]
	v_pk_mul_f32 v[40:41], v[204:205], v[40:41]
	v_pk_mul_f32 v[42:43], v[206:207], v[42:43]
	v_pk_mul_f32 v[184:185], v[184:185], v[36:37]
	v_pk_mul_f32 v[186:187], v[186:187], v[38:39]
	v_pk_mul_f32 v[188:189], v[188:189], v[40:41]
	v_pk_mul_f32 v[190:191], v[190:191], v[42:43]
	v_pk_fma_f32 v[44:45], v[184:185], v[184:185], v[44:45]
	v_pk_fma_f32 v[44:45], v[186:187], v[186:187], v[44:45]
; __device__ __forceinline__ float siluf_(float x) { return x * __builtin_amdgcn_rcpf(1.f + __expf(-x)); }
; __device__ __forceinline__ void mix_finalize_ssd(size_t row, bf16_t* MIX, const bf16_t* XBC, const bf16_t* PROJ, const float* d_skip, const float* ssd_norm_w, int lane, bf16_t* ssd_dst) {
;     ...
;         for (int k = 0; k < 4; ++k) { float f[8], xf[8], zf[8]; unpack8(yv[k], f); unpack8(xv[k], xf); unpack8(zv[k], zf);
; #pragma unroll
;             for (int e = 0; e < 8; ++e) { f[e] = (f[e] + dsk[k] * xf[e]) * siluf_(zf[e]); s += f[e] * f[e]; }
;             yv[k] = pack8(f); }
; __global__ void __launch_bounds__(512, 2) mk_fwd(Args args) {
;     ...
;             const u32x4 yv = *(const u32x4*)(mp + c), xv = *(const u32x4*)(XBC + m * XBCW + c), zv = *(const u32x4*)(PROJ + m * NPROJ + CZ + c);
;             const float dsk = d_skip[c >> 6]; const f32x4 w0 = *(const f32x4*)(ssd_norm_w + c), w1 = *(const f32x4*)(ssd_norm_w + c + 4);
;             float f[8], xf[8], zf[8]; unpack8(yv, f); unpack8(xv, xf); unpack8(zv, zf);
;             float sq = 0.f;
; #pragma unroll
;             for (int e = 0; e < 8; ++e) { f[e] = (f[e] + dsk * xf[e]) * siluf_(zf[e]); sq += f[e] * f[e]; }
	v_pk_fma_f32 v[44:45], v[188:189], v[188:189], v[44:45]
	v_pk_fma_f32 v[44:45], v[190:191], v[190:191], v[44:45]
	v_cvt_pk_bf16_f32 v156, v184, v185
	v_cvt_pk_bf16_f32 v157, v186, v187
	v_cvt_pk_bf16_f32 v158, v188, v189
	v_cvt_pk_bf16_f32 v159, v190, v191
	v_lshlrev_b32_e32 v184, 16, v64
	v_and_b32_e32 v185, 0xffff0000, v64
	v_lshlrev_b32_e32 v186, 16, v65
	v_and_b32_e32 v187, 0xffff0000, v65
	v_lshlrev_b32_e32 v188, 16, v66
	v_and_b32_e32 v189, 0xffff0000, v66
	v_lshlrev_b32_e32 v190, 16, v67
	v_and_b32_e32 v191, 0xffff0000, v67
	v_lshlrev_b32_e32 v192, 16, v80
	v_and_b32_e32 v193, 0xffff0000, v80
	v_lshlrev_b32_e32 v194, 16, v81
	v_and_b32_e32 v195, 0xffff0000, v81
	v_lshlrev_b32_e32 v196, 16, v82
	v_and_b32_e32 v197, 0xffff0000, v82
	v_lshlrev_b32_e32 v198, 16, v83
	v_and_b32_e32 v199, 0xffff0000, v83
	v_lshlrev_b32_e32 v200, 16, v96
	v_and_b32_e32 v201, 0xffff0000, v96
	v_lshlrev_b32_e32 v202, 16, v97
	v_and_b32_e32 v203, 0xffff0000, v97
	v_lshlrev_b32_e32 v204, 16, v98
	v_and_b32_e32 v205, 0xffff0000, v98
	v_lshlrev_b32_e32 v206, 16, v99
	v_and_b32_e32 v207, 0xffff0000, v99
	v_pk_fma_f32 v[184:185], v[192:193], v[34:35], v[184:185] op_sel:[0,0,0] op_sel_hi:[1,0,1]
	v_pk_fma_f32 v[186:187], v[194:195], v[34:35], v[186:187] op_sel:[0,0,0] op_sel_hi:[1,0,1]
	v_pk_fma_f32 v[188:189], v[196:197], v[34:35], v[188:189] op_sel:[0,0,0] op_sel_hi:[1,0,1]
	v_pk_fma_f32 v[190:191], v[198:199], v[34:35], v[190:191] op_sel:[0,0,0] op_sel_hi:[1,0,1]
	v_pk_mul_f32 v[36:37], v[200:201], v[46:47] op_sel:[0,0] op_sel_hi:[1,0]
	v_pk_mul_f32 v[38:39], v[202:203], v[46:47] op_sel:[0,0] op_sel_hi:[1,0]
	v_pk_mul_f32 v[40:41], v[204:205], v[46:47] op_sel:[0,0] op_sel_hi:[1,0]
	v_pk_mul_f32 v[42:43], v[206:207], v[46:47] op_sel:[0,0] op_sel_hi:[1,0]
	v_exp_f32_e32 v36, v36
	v_exp_f32_e32 v37, v37
	v_exp_f32_e32 v38, v38
	v_exp_f32_e32 v39, v39
	v_exp_f32_e32 v40, v40
	v_exp_f32_e32 v41, v41
	v_exp_f32_e32 v42, v42
	v_exp_f32_e32 v43, v43
	v_pk_add_f32 v[36:37], v[36:37], v[46:47] op_sel:[0,1] op_sel_hi:[1,1]
	v_pk_add_f32 v[38:39], v[38:39], v[46:47] op_sel:[0,1] op_sel_hi:[1,1]
	v_pk_add_f32 v[40:41], v[40:41], v[46:47] op_sel:[0,1] op_sel_hi:[1,1]
	v_pk_add_f32 v[42:43], v[42:43], v[46:47] op_sel:[0,1] op_sel_hi:[1,1]
	v_rcp_f32_e32 v36, v36
	v_rcp_f32_e32 v37, v37
	v_rcp_f32_e32 v38, v38
	v_rcp_f32_e32 v39, v39
	v_rcp_f32_e32 v40, v40
	v_rcp_f32_e32 v41, v41
	v_rcp_f32_e32 v42, v42
	v_rcp_f32_e32 v43, v43
	v_pk_mul_f32 v[36:37], v[200:201], v[36:37]
	v_pk_mul_f32 v[38:39], v[202:203], v[38:39]
	v_pk_mul_f32 v[40:41], v[204:205], v[40:41]
	v_pk_mul_f32 v[42:43], v[206:207], v[42:43]
	v_pk_mul_f32 v[184:185], v[184:185], v[36:37]
	v_pk_mul_f32 v[186:187], v[186:187], v[38:39]
	v_pk_mul_f32 v[188:189], v[188:189], v[40:41]
	v_pk_mul_f32 v[190:191], v[190:191], v[42:43]
	v_pk_fma_f32 v[44:45], v[184:185], v[184:185], v[44:45]
	v_pk_fma_f32 v[44:45], v[186:187], v[186:187], v[44:45]
	v_pk_fma_f32 v[44:45], v[188:189], v[188:189], v[44:45]
	v_pk_fma_f32 v[44:45], v[190:191], v[190:191], v[44:45]
	v_cvt_pk_bf16_f32 v160, v184, v185
	v_cvt_pk_bf16_f32 v161, v186, v187
	v_cvt_pk_bf16_f32 v162, v188, v189
	v_cvt_pk_bf16_f32 v163, v190, v191
	v_lshlrev_b32_e32 v184, 16, v68
	v_and_b32_e32 v185, 0xffff0000, v68
	v_lshlrev_b32_e32 v186, 16, v69
	v_and_b32_e32 v187, 0xffff0000, v69
	v_lshlrev_b32_e32 v188, 16, v70
	v_and_b32_e32 v189, 0xffff0000, v70
	v_lshlrev_b32_e32 v190, 16, v71
	v_and_b32_e32 v191, 0xffff0000, v71
	v_lshlrev_b32_e32 v192, 16, v84
	v_and_b32_e32 v193, 0xffff0000, v84
	v_lshlrev_b32_e32 v194, 16, v85
	v_and_b32_e32 v195, 0xffff0000, v85
	v_lshlrev_b32_e32 v196, 16, v86
	v_and_b32_e32 v197, 0xffff0000, v86
	v_lshlrev_b32_e32 v198, 16, v87
	v_and_b32_e32 v199, 0xffff0000, v87
	v_lshlrev_b32_e32 v200, 16, v100
	v_and_b32_e32 v201, 0xffff0000, v100
	v_lshlrev_b32_e32 v202, 16, v101
	v_and_b32_e32 v203, 0xffff0000, v101
	v_lshlrev_b32_e32 v204, 16, v102
	v_and_b32_e32 v205, 0xffff0000, v102
	v_lshlrev_b32_e32 v206, 16, v103
	v_and_b32_e32 v207, 0xffff0000, v103
	v_pk_fma_f32 v[184:185], v[192:193], v[34:35], v[184:185] op_sel:[0,1,0] op_sel_hi:[1,1,1]
	v_pk_fma_f32 v[186:187], v[194:195], v[34:35], v[186:187] op_sel:[0,1,0] op_sel_hi:[1,1,1]
	v_pk_fma_f32 v[188:189], v[196:197], v[34:35], v[188:189] op_sel:[0,1,0] op_sel_hi:[1,1,1]
	v_pk_fma_f32 v[190:191], v[198:199], v[34:35], v[190:191] op_sel:[0,1,0] op_sel_hi:[1,1,1]
	v_pk_mul_f32 v[36:37], v[200:201], v[46:47] op_sel:[0,0] op_sel_hi:[1,0]
	v_pk_mul_f32 v[38:39], v[202:203], v[46:47] op_sel:[0,0] op_sel_hi:[1,0]
	v_pk_mul_f32 v[40:41], v[204:205], v[46:47] op_sel:[0,0] op_sel_hi:[1,0]
	v_pk_mul_f32 v[42:43], v[206:207], v[46:47] op_sel:[0,0] op_sel_hi:[1,0]
	v_exp_f32_e32 v36, v36
	v_exp_f32_e32 v37, v37
	v_exp_f32_e32 v38, v38
	v_exp_f32_e32 v39, v39
	v_exp_f32_e32 v40, v40
	v_exp_f32_e32 v41, v41
	v_exp_f32_e32 v42, v42
	v_exp_f32_e32 v43, v43
	v_pk_add_f32 v[36:37], v[36:37], v[46:47] op_sel:[0,1] op_sel_hi:[1,1]
	v_pk_add_f32 v[38:39], v[38:39], v[46:47] op_sel:[0,1] op_sel_hi:[1,1]
	v_pk_add_f32 v[40:41], v[40:41], v[46:47] op_sel:[0,1] op_sel_hi:[1,1]
	v_pk_add_f32 v[42:43], v[42:43], v[46:47] op_sel:[0,1] op_sel_hi:[1,1]
	v_rcp_f32_e32 v36, v36
	v_rcp_f32_e32 v37, v37
	v_rcp_f32_e32 v38, v38
	v_rcp_f32_e32 v39, v39
	v_rcp_f32_e32 v40, v40
	v_rcp_f32_e32 v41, v41
	v_rcp_f32_e32 v42, v42
	v_rcp_f32_e32 v43, v43
; __device__ __forceinline__ void mix_finalize_ssd(size_t row, bf16_t* MIX, const bf16_t* XBC, const bf16_t* PROJ, const float* d_skip, const float* ssd_norm_w, int lane, bf16_t* ssd_dst) {
;     ...
;         const float r = rsqrtf(wave_sum(s) * (1.f / DM) + EPS);
; #pragma unroll 1
;         for (int k = 0; k < 4; ++k) { const int c = (k * 64 + lane) * 8;
;             const f32x4 w0 = *(const f32x4*)(ssd_norm_w + c), w1 = *(const f32x4*)(ssd_norm_w + c + 4);
;             const u32x4 yk = (k == 0) ? yv[0] : (k == 1) ? yv[1] : (k == 2) ? yv[2] : yv[3];
;             float f[8]; unpack8(yk, f);
;             float o[8]; o[0] = f[0] * r * w0.x; o[1] = f[1] * r * w0.y; o[2] = f[2] * r * w0.z; o[3] = f[3] * r * w0.w;
;             o[4] = f[4] * r * w1.x; o[5] = f[5] * r * w1.y; o[6] = f[6] * r * w1.z; o[7] = f[7] * r * w1.w;
;             *(u32x4*)(ssd_dst + c) = pack8(o); }
; __global__ void __launch_bounds__(512, 2) mk_fwd(Args args) {
;     ...
;             float o[8]; o[0] = f[0] * r * w0.x; o[1] = f[1] * r * w0.y; o[2] = f[2] * r * w0.z; o[3] = f[3] * r * w0.w; o[4] = f[4] * r * w1.x; o[5] = f[5] * r * w1.y; o[6] = f[6] * r * w1.z; o[7] = f[7] * r * w1.w;
;             bf16_t* dst = (psel == 3) ? XN + m * DM : mp;
;             *(u32x4*)(dst + c) = pack8(o);
	v_pk_mul_f32 v[36:37], v[200:201], v[36:37]
	v_pk_mul_f32 v[38:39], v[202:203], v[38:39]
	v_pk_mul_f32 v[40:41], v[204:205], v[40:41]
	v_pk_mul_f32 v[42:43], v[206:207], v[42:43]
	v_pk_mul_f32 v[184:185], v[184:185], v[36:37]
	v_pk_mul_f32 v[186:187], v[186:187], v[38:39]
	v_pk_mul_f32 v[188:189], v[188:189], v[40:41]
	v_pk_mul_f32 v[190:191], v[190:191], v[42:43]
	v_pk_fma_f32 v[44:45], v[184:185], v[184:185], v[44:45]
	v_pk_fma_f32 v[44:45], v[186:187], v[186:187], v[44:45]
	v_pk_fma_f32 v[44:45], v[188:189], v[188:189], v[44:45]
	v_pk_fma_f32 v[44:45], v[190:191], v[190:191], v[44:45]
	v_cvt_pk_bf16_f32 v164, v184, v185
	v_cvt_pk_bf16_f32 v165, v186, v187
	v_cvt_pk_bf16_f32 v166, v188, v189
	v_cvt_pk_bf16_f32 v167, v190, v191
	v_add_f32_e32 v208, v44, v45
	s_nop 1
	v_add_f32_dpp v209, v208, v208 quad_perm:[1,0,3,2] row_mask:0xf bank_mask:0xf
	s_nop 1
	v_add_f32_dpp v208, v209, v209 quad_perm:[2,3,0,1] row_mask:0xf bank_mask:0xf
	s_nop 1
	v_add_f32_dpp v209, v208, v208 row_half_mirror row_mask:0xf bank_mask:0xf
	s_nop 1
	v_add_f32_dpp v208, v209, v209 row_mirror row_mask:0xf bank_mask:0xf
	s_nop 1
	v_readlane_b32 s10, v208, 0
	v_readlane_b32 s11, v208, 16
	v_readlane_b32 s17, v208, 32
	v_readlane_b32 s24, v208, 48
	s_nop 3
	v_mov_b32_e32 v208, s10
	v_add_f32_e32 v208, s11, v208
	v_add_f32_e32 v208, s17, v208
	v_add_f32_e32 v208, s24, v208
	v_fmamk_f32 v208, v208, 0x3a000000, v48
	v_rsq_f32_e32 v49, v208
	s_nop 0
	v_lshlrev_b32_e32 v184, 16, v152
	v_and_b32_e32 v185, 0xffff0000, v152
	v_lshlrev_b32_e32 v186, 16, v153
	v_and_b32_e32 v187, 0xffff0000, v153
	v_lshlrev_b32_e32 v188, 16, v154
	v_and_b32_e32 v189, 0xffff0000, v154
	v_lshlrev_b32_e32 v190, 16, v155
	v_and_b32_e32 v191, 0xffff0000, v155
	v_pk_mul_f32 v[184:185], v[184:185], v[48:49] op_sel:[0,1] op_sel_hi:[1,1]
	v_pk_mul_f32 v[186:187], v[186:187], v[48:49] op_sel:[0,1] op_sel_hi:[1,1]
	v_pk_mul_f32 v[188:189], v[188:189], v[48:49] op_sel:[0,1] op_sel_hi:[1,1]
	v_pk_mul_f32 v[190:191], v[190:191], v[48:49] op_sel:[0,1] op_sel_hi:[1,1]
	v_pk_mul_f32 v[184:185], v[184:185], v[0:1]
	v_pk_mul_f32 v[186:187], v[186:187], v[2:3]
	v_pk_mul_f32 v[188:189], v[188:189], v[4:5]
	v_pk_mul_f32 v[190:191], v[190:191], v[6:7]
	v_cvt_pk_bf16_f32 v168, v184, v185
	v_cvt_pk_bf16_f32 v169, v186, v187
	v_cvt_pk_bf16_f32 v170, v188, v189
	v_cvt_pk_bf16_f32 v171, v190, v191
	global_store_dwordx4 v50, v[168:171], s[26:27] offset:0
	v_lshlrev_b32_e32 v184, 16, v156
	v_and_b32_e32 v185, 0xffff0000, v156
	v_lshlrev_b32_e32 v186, 16, v157
	v_and_b32_e32 v187, 0xffff0000, v157
	v_lshlrev_b32_e32 v188, 16, v158
	v_and_b32_e32 v189, 0xffff0000, v158
	v_lshlrev_b32_e32 v190, 16, v159
	v_and_b32_e32 v191, 0xffff0000, v159
	v_pk_mul_f32 v[184:185], v[184:185], v[48:49] op_sel:[0,1] op_sel_hi:[1,1]
	v_pk_mul_f32 v[186:187], v[186:187], v[48:49] op_sel:[0,1] op_sel_hi:[1,1]
	v_pk_mul_f32 v[188:189], v[188:189], v[48:49] op_sel:[0,1] op_sel_hi:[1,1]
	v_pk_mul_f32 v[190:191], v[190:191], v[48:49] op_sel:[0,1] op_sel_hi:[1,1]
	v_pk_mul_f32 v[184:185], v[184:185], v[8:9]
	v_pk_mul_f32 v[186:187], v[186:187], v[10:11]
	v_pk_mul_f32 v[188:189], v[188:189], v[12:13]
	v_pk_mul_f32 v[190:191], v[190:191], v[14:15]
	v_cvt_pk_bf16_f32 v172, v184, v185
	v_cvt_pk_bf16_f32 v173, v186, v187
	v_cvt_pk_bf16_f32 v174, v188, v189
	v_cvt_pk_bf16_f32 v175, v190, v191
	global_store_dwordx4 v50, v[172:175], s[26:27] offset:1024
	v_lshlrev_b32_e32 v184, 16, v160
	v_and_b32_e32 v185, 0xffff0000, v160
	v_lshlrev_b32_e32 v186, 16, v161
	v_and_b32_e32 v187, 0xffff0000, v161
	v_lshlrev_b32_e32 v188, 16, v162
	v_and_b32_e32 v189, 0xffff0000, v162
	v_lshlrev_b32_e32 v190, 16, v163
	v_and_b32_e32 v191, 0xffff0000, v163
	v_pk_mul_f32 v[184:185], v[184:185], v[48:49] op_sel:[0,1] op_sel_hi:[1,1]
	v_pk_mul_f32 v[186:187], v[186:187], v[48:49] op_sel:[0,1] op_sel_hi:[1,1]
	v_pk_mul_f32 v[188:189], v[188:189], v[48:49] op_sel:[0,1] op_sel_hi:[1,1]
	v_pk_mul_f32 v[190:191], v[190:191], v[48:49] op_sel:[0,1] op_sel_hi:[1,1]
	v_pk_mul_f32 v[184:185], v[184:185], v[16:17]
	v_pk_mul_f32 v[186:187], v[186:187], v[18:19]
	v_pk_mul_f32 v[188:189], v[188:189], v[20:21]
	v_pk_mul_f32 v[190:191], v[190:191], v[22:23]
	v_cvt_pk_bf16_f32 v176, v184, v185
	v_cvt_pk_bf16_f32 v177, v186, v187
	v_cvt_pk_bf16_f32 v178, v188, v189
	v_cvt_pk_bf16_f32 v179, v190, v191
	global_store_dwordx4 v50, v[176:179], s[26:27] offset:2048
	v_lshlrev_b32_e32 v184, 16, v164
	v_and_b32_e32 v185, 0xffff0000, v164
	v_lshlrev_b32_e32 v186, 16, v165
	v_and_b32_e32 v187, 0xffff0000, v165
	v_lshlrev_b32_e32 v188, 16, v166
	v_and_b32_e32 v189, 0xffff0000, v166
	v_lshlrev_b32_e32 v190, 16, v167
	v_and_b32_e32 v191, 0xffff0000, v167
	v_pk_mul_f32 v[184:185], v[184:185], v[48:49] op_sel:[0,1] op_sel_hi:[1,1]
	v_pk_mul_f32 v[186:187], v[186:187], v[48:49] op_sel:[0,1] op_sel_hi:[1,1]
	v_pk_mul_f32 v[188:189], v[188:189], v[48:49] op_sel:[0,1] op_sel_hi:[1,1]
	v_pk_mul_f32 v[190:191], v[190:191], v[48:49] op_sel:[0,1] op_sel_hi:[1,1]
	v_pk_mul_f32 v[184:185], v[184:185], v[24:25]
	v_pk_mul_f32 v[186:187], v[186:187], v[26:27]
	v_pk_mul_f32 v[188:189], v[188:189], v[28:29]
	v_pk_mul_f32 v[190:191], v[190:191], v[30:31]
	v_cvt_pk_bf16_f32 v180, v184, v185
	v_cvt_pk_bf16_f32 v181, v186, v187
	v_cvt_pk_bf16_f32 v182, v188, v189
	v_cvt_pk_bf16_f32 v183, v190, v191
	global_store_dwordx4 v50, v[180:183], s[26:27] offset:3072
	s_branch .LBB0_561
